# v32 + sc1 (write-through) on the weight conversion's bf16 output stores issued by idle workgroups during the WO/DOWN GEMM phases
# speedup vs baseline: 1.0097x; 1.0019x over previous
.LBB0_1020:
	s_add_i32 s11, s11, s9
	v_add_u32_e32 v6, s11, v20
	s_ashr_i32 s15, s14, 31
	v_ashrrev_i32_e32 v7, 31, v6
	s_mov_b32 s57, s56
	v_lshl_add_u64 v[8:9], s[14:15], 1, v[4:5]
	v_lshlrev_b64 v[14:15], 13, v[6:7]
	s_mov_b32 s58, s56
	s_mov_b32 s59, s56
	v_mov_b64_e32 v[16:17], s[56:57]
	v_lshl_add_u64 v[14:15], v[8:9], 0, v[14:15]
	v_mov_b64_e32 v[18:19], s[58:59]
	global_store_dwordx4 v[14:15], v[16:19], off sc1
	v_add_u32_e32 v14, 8, v6
	v_ashrrev_i32_e32 v15, 31, v14
	v_lshlrev_b64 v[14:15], 13, v[14:15]
	v_lshl_add_u64 v[14:15], v[8:9], 0, v[14:15]
	global_store_dwordx4 v[14:15], v[16:19], off sc1
	v_add_u32_e32 v14, 16, v6
	v_add_u32_e32 v6, 24, v6
	v_ashrrev_i32_e32 v15, 31, v14
	v_ashrrev_i32_e32 v7, 31, v6
	v_lshlrev_b64 v[14:15], 13, v[14:15]
	v_lshlrev_b64 v[6:7], 13, v[6:7]
	v_lshl_add_u64 v[14:15], v[8:9], 0, v[14:15]
	v_lshl_add_u64 v[6:7], v[8:9], 0, v[6:7]
	global_store_dwordx4 v[14:15], v[16:19], off sc1
	global_store_dwordx4 v[6:7], v[16:19], off sc1

.LBB0_1022:
	s_ashr_i32 s11, s10, 31
	s_lshr_b32 s11, s11, 27
	s_add_i32 s11, s10, s11
	s_ashr_i32 s11, s11, 5
	s_lshl_b32 s14, s11, 6
	s_lshl_b32 s11, s11, 10
	s_andn2_b64 vcc, exec, s[6:7]
	s_sub_i32 s11, 0, s11
	s_cbranch_vccnz .LBB0_1024
	s_add_i32 s18, s9, s11
	v_or_b32_e32 v18, s14, v20
	s_ashr_i32 s19, s18, 31
	v_ashrrev_i32_e32 v19, 31, v18
	v_or_b32_e32 v14, 8, v18
	v_or_b32_e32 v26, 16, v18
	v_lshl_add_u64 v[46:47], s[18:19], 2, v[2:3]
	v_lshlrev_b64 v[6:7], 12, v[18:19]
	v_ashrrev_i32_e32 v15, 31, v14
	v_ashrrev_i32_e32 v27, 31, v26
	v_lshl_add_u64 v[6:7], v[46:47], 0, v[6:7]
	v_lshlrev_b64 v[14:15], 12, v[14:15]
	v_lshlrev_b64 v[26:27], 12, v[26:27]
	v_or_b32_e32 v30, 24, v18
	global_load_dwordx4 v[6:9], v[6:7], off nt
	v_lshl_add_u64 v[14:15], v[46:47], 0, v[14:15]
	v_lshl_add_u64 v[26:27], v[46:47], 0, v[26:27]
	v_ashrrev_i32_e32 v31, 31, v30
	v_or_b32_e32 v34, 32, v18
	global_load_dwordx4 v[14:17], v[14:15], off nt
	v_lshlrev_b64 v[30:31], 12, v[30:31]
	global_load_dwordx4 v[26:29], v[26:27], off nt
	v_ashrrev_i32_e32 v35, 31, v34
	v_lshl_add_u64 v[30:31], v[46:47], 0, v[30:31]
	v_lshlrev_b64 v[34:35], 12, v[34:35]
	v_or_b32_e32 v38, 40, v18
	global_load_dwordx4 v[30:33], v[30:31], off nt
	v_lshl_add_u64 v[34:35], v[46:47], 0, v[34:35]
	v_ashrrev_i32_e32 v39, 31, v38
	global_load_dwordx4 v[34:37], v[34:35], off nt
	v_lshlrev_b64 v[38:39], 12, v[38:39]
	v_or_b32_e32 v42, 48, v18
	v_lshl_add_u64 v[38:39], v[46:47], 0, v[38:39]
	v_ashrrev_i32_e32 v43, 31, v42
	global_load_dwordx4 v[38:41], v[38:39], off nt
	v_lshlrev_b64 v[42:43], 12, v[42:43]
	v_or_b32_e32 v18, 56, v18
	v_lshl_add_u64 v[42:43], v[46:47], 0, v[42:43]
	v_ashrrev_i32_e32 v19, 31, v18
	global_load_dwordx4 v[42:45], v[42:43], off nt
	v_lshlrev_b64 v[18:19], 12, v[18:19]
	v_lshl_add_u64 v[18:19], v[46:47], 0, v[18:19]
	global_load_dwordx4 v[46:49], v[18:19], off nt
	v_add_u32_e32 v0, v21, v23
	s_ashr_i32 s15, s14, 31
	s_waitcnt vmcnt(7)
	ds_write2_b32 v22, v6, v7 offset1:1
	ds_write2_b32 v22, v8, v9 offset0:2 offset1:3
	v_add_u32_e32 v6, 0x420, v0
	s_waitcnt vmcnt(6)
	ds_write2_b32 v0, v14, v15 offset1:1
	ds_write2_b32 v0, v16, v17 offset0:2 offset1:3
	s_waitcnt vmcnt(5)
	ds_write2_b32 v6, v26, v27 offset1:1
	v_add_u32_e32 v6, 0x428, v0
	ds_write2_b32 v6, v28, v29 offset1:1
	v_add_u32_e32 v6, 0x840, v0
	v_add_u32_e32 v0, 0x848, v0
	s_waitcnt vmcnt(4)
	ds_write2_b32 v0, v32, v33 offset1:1
	v_add_u32_e32 v0, 0x1080, v22
	ds_write2_b32 v6, v30, v31 offset1:1
	s_waitcnt vmcnt(3)
	ds_write2_b32 v0, v34, v35 offset1:1
	v_add_u32_e32 v0, 0x1088, v22
	ds_write2_b32 v0, v36, v37 offset1:1
	v_add_u32_e32 v0, 0x14a0, v22
	v_lshl_add_u64 v[6:7], s[14:15], 1, v[4:5]
	s_waitcnt vmcnt(2)
	ds_write2_b32 v0, v38, v39 offset1:1
	v_add_u32_e32 v0, 0x14a8, v22
	ds_write2_b32 v0, v40, v41 offset1:1
	v_add_u32_e32 v0, 0x18c0, v22
	v_add_u32_e32 v38, s18, v20
	s_waitcnt vmcnt(1)
	ds_write2_b32 v0, v42, v43 offset1:1
	v_add_u32_e32 v0, 0x18c8, v22
	ds_write2_b32 v0, v44, v45 offset1:1
	v_add_u32_e32 v0, 0x1ce0, v22
	s_waitcnt vmcnt(0)
	ds_write2_b32 v0, v46, v47 offset1:1
	v_add_u32_e32 v0, 0x1ce8, v22
	ds_write2_b32 v0, v48, v49 offset1:1
	s_waitcnt lgkmcnt(0)
	ds_read2_b32 v[8:9], v24 offset0:33 offset1:41
	ds_read2_b32 v[18:19], v24 offset1:8
	ds_read2_b32 v[26:27], v24 offset0:66 offset1:74
	ds_read2_b32 v[28:29], v24 offset0:99 offset1:107
	ds_read2_b32 v[30:31], v24 offset0:132 offset1:140
	ds_read2_b32 v[32:33], v24 offset0:165 offset1:173
	ds_read2_b32 v[34:35], v24 offset0:198 offset1:206
	ds_read2_b32 v[36:37], v24 offset0:231 offset1:239
	v_ashrrev_i32_e32 v39, 31, v38
	v_lshlrev_b64 v[40:41], 13, v[38:39]
	s_waitcnt lgkmcnt(6)
	v_cvt_pk_bf16_f32 v14, v18, v8
	s_waitcnt lgkmcnt(4)
	v_cvt_pk_bf16_f32 v15, v26, v28
	s_waitcnt lgkmcnt(2)
	v_cvt_pk_bf16_f32 v16, v30, v32
	s_waitcnt lgkmcnt(0)
	v_cvt_pk_bf16_f32 v17, v34, v36
	v_lshl_add_u64 v[40:41], v[6:7], 0, v[40:41]
	v_add_u32_e32 v8, 8, v38
	global_store_dwordx4 v[40:41], v[14:17], off sc1
	v_add_u32_e32 v40, 16, v38
	v_ashrrev_i32_e32 v41, 31, v40
	v_cvt_pk_bf16_f32 v14, v19, v9
	v_ashrrev_i32_e32 v9, 31, v8
	v_lshlrev_b64 v[8:9], 13, v[8:9]
	v_cvt_pk_bf16_f32 v15, v27, v29
	v_cvt_pk_bf16_f32 v16, v31, v33
	v_cvt_pk_bf16_f32 v17, v35, v37
	v_lshl_add_u64 v[8:9], v[6:7], 0, v[8:9]
	global_store_dwordx4 v[8:9], v[14:17], off sc1
	ds_read2_b32 v[8:9], v24 offset0:49 offset1:57
	ds_read2_b32 v[18:19], v24 offset0:16 offset1:24
	ds_read2_b32 v[26:27], v24 offset0:82 offset1:90
	ds_read2_b32 v[28:29], v24 offset0:115 offset1:123
	ds_read2_b32 v[30:31], v24 offset0:148 offset1:156
	ds_read2_b32 v[32:33], v24 offset0:181 offset1:189
	ds_read2_b32 v[34:35], v24 offset0:214 offset1:222
	ds_read2_b32 v[36:37], v24 offset0:247 offset1:255
	v_lshlrev_b64 v[40:41], 13, v[40:41]
	s_waitcnt lgkmcnt(6)
	v_cvt_pk_bf16_f32 v14, v18, v8
	s_waitcnt lgkmcnt(4)
	v_cvt_pk_bf16_f32 v15, v26, v28
	s_waitcnt lgkmcnt(2)
	v_cvt_pk_bf16_f32 v16, v30, v32
	s_waitcnt lgkmcnt(0)
	v_cvt_pk_bf16_f32 v17, v34, v36
	v_lshl_add_u64 v[40:41], v[6:7], 0, v[40:41]
	v_add_u32_e32 v8, 24, v38
	global_store_dwordx4 v[40:41], v[14:17], off sc1
	s_nop 1
	v_cvt_pk_bf16_f32 v14, v19, v9
	v_ashrrev_i32_e32 v9, 31, v8
	v_lshlrev_b64 v[8:9], 13, v[8:9]
	v_cvt_pk_bf16_f32 v15, v27, v29
	v_cvt_pk_bf16_f32 v16, v31, v33
	v_cvt_pk_bf16_f32 v17, v35, v37
	v_lshl_add_u64 v[6:7], v[6:7], 0, v[8:9]
	global_store_dwordx4 v[6:7], v[14:17], off sc1
	s_waitcnt lgkmcnt(0)
	s_cbranch_execnz .LBB0_1021
	s_branch .LBB0_1020

.LBB0_1028:
	s_add_i32 s11, s11, s9
	v_add_u32_e32 v6, s11, v20
	s_ashr_i32 s19, s18, 31
	v_ashrrev_i32_e32 v7, 31, v6
	s_mov_b32 s57, s56
	v_lshl_add_u64 v[8:9], s[18:19], 1, v[4:5]
	v_lshlrev_b64 v[14:15], 11, v[6:7]
	s_mov_b32 s58, s56
	s_mov_b32 s59, s56
	v_mov_b64_e32 v[16:17], s[56:57]
	v_lshl_add_u64 v[14:15], v[8:9], 0, v[14:15]
	v_mov_b64_e32 v[18:19], s[58:59]
	global_store_dwordx4 v[14:15], v[16:19], off sc1
	v_add_u32_e32 v14, 8, v6
	v_ashrrev_i32_e32 v15, 31, v14
	v_lshlrev_b64 v[14:15], 11, v[14:15]
	v_lshl_add_u64 v[14:15], v[8:9], 0, v[14:15]
	global_store_dwordx4 v[14:15], v[16:19], off sc1
	v_add_u32_e32 v14, 16, v6
	v_add_u32_e32 v6, 24, v6
	v_ashrrev_i32_e32 v15, 31, v14
	v_ashrrev_i32_e32 v7, 31, v6
	v_lshlrev_b64 v[14:15], 11, v[14:15]
	v_lshlrev_b64 v[6:7], 11, v[6:7]
	v_lshl_add_u64 v[14:15], v[8:9], 0, v[14:15]
	v_lshl_add_u64 v[6:7], v[8:9], 0, v[6:7]
	global_store_dwordx4 v[14:15], v[16:19], off sc1
	global_store_dwordx4 v[6:7], v[16:19], off sc1

.LBB0_1030:
	s_mul_hi_i32 s11, s10, 0x2aaaaaab
	s_lshr_b32 s12, s11, 31
	s_ashr_i32 s11, s11, 3
	s_add_i32 s11, s11, s12
	s_lshl_b32 s18, s11, 6
	s_andn2_b64 vcc, exec, s[14:15]
	s_mulk_i32 s11, 0xfa00
	s_cbranch_vccnz .LBB0_1032
	s_add_i32 s24, s9, s11
	v_or_b32_e32 v0, s18, v20
	s_ashr_i32 s25, s24, 31
	v_lshl_add_u64 v[18:19], s[24:25], 2, v[2:3]
	v_or_b32_e32 v11, 8, v0
	v_mad_i64_i32 v[6:7], s[12:13], v0, s76, v[18:19]
	v_mad_i64_i32 v[14:15], s[12:13], v11, s76, v[18:19]
	v_or_b32_e32 v11, 16, v0
	global_load_dwordx4 v[6:9], v[6:7], off nt
	v_mad_i64_i32 v[26:27], s[12:13], v11, s76, v[18:19]
	global_load_dwordx4 v[14:17], v[14:15], off nt
	v_or_b32_e32 v11, 24, v0
	global_load_dwordx4 v[26:29], v[26:27], off nt
	v_mad_i64_i32 v[30:31], s[12:13], v11, s76, v[18:19]
	v_or_b32_e32 v11, 32, v0
	global_load_dwordx4 v[30:33], v[30:31], off nt
	v_mad_i64_i32 v[34:35], s[12:13], v11, s76, v[18:19]
	global_load_dwordx4 v[34:37], v[34:35], off nt
	v_or_b32_e32 v11, 40, v0
	v_mad_i64_i32 v[38:39], s[12:13], v11, s76, v[18:19]
	global_load_dwordx4 v[38:41], v[38:39], off nt
	v_or_b32_e32 v11, 48, v0
	v_mad_i64_i32 v[42:43], s[12:13], v11, s76, v[18:19]
	global_load_dwordx4 v[42:45], v[42:43], off nt
	v_or_b32_e32 v0, 56, v0
	v_mad_i64_i32 v[18:19], s[12:13], v0, s76, v[18:19]
	global_load_dwordx4 v[46:49], v[18:19], off nt
	v_add_u32_e32 v0, v21, v23
	s_ashr_i32 s19, s18, 31
	s_waitcnt vmcnt(7)
	ds_write2_b32 v22, v6, v7 offset1:1
	ds_write2_b32 v22, v8, v9 offset0:2 offset1:3
	v_add_u32_e32 v6, 0x420, v0
	s_waitcnt vmcnt(6)
	ds_write2_b32 v0, v14, v15 offset1:1
	ds_write2_b32 v0, v16, v17 offset0:2 offset1:3
	v_add_u32_e32 v8, s24, v20
	s_waitcnt vmcnt(5)
	ds_write2_b32 v6, v26, v27 offset1:1
	v_add_u32_e32 v6, 0x428, v0
	ds_write2_b32 v6, v28, v29 offset1:1
	v_add_u32_e32 v6, 0x840, v0
	v_add_u32_e32 v0, 0x848, v0
	s_waitcnt vmcnt(4)
	ds_write2_b32 v0, v32, v33 offset1:1
	v_add_u32_e32 v0, 0x1080, v22
	s_waitcnt vmcnt(3)
	ds_write2_b32 v0, v34, v35 offset1:1
	v_add_u32_e32 v0, 0x1088, v22
	ds_write2_b32 v0, v36, v37 offset1:1
	v_add_u32_e32 v0, 0x14a0, v22
	s_waitcnt vmcnt(2)
	ds_write2_b32 v0, v38, v39 offset1:1
	v_add_u32_e32 v0, 0x14a8, v22
	ds_write2_b32 v0, v40, v41 offset1:1
	v_add_u32_e32 v0, 0x18c0, v22
	s_waitcnt vmcnt(1)
	ds_write2_b32 v0, v42, v43 offset1:1
	v_add_u32_e32 v0, 0x18c8, v22
	ds_write2_b32 v0, v44, v45 offset1:1
	v_add_u32_e32 v0, 0x1ce0, v22
	s_waitcnt vmcnt(0)
	ds_write2_b32 v0, v46, v47 offset1:1
	v_add_u32_e32 v0, 0x1ce8, v22
	ds_write2_b32 v6, v30, v31 offset1:1
	ds_write2_b32 v0, v48, v49 offset1:1
	s_waitcnt lgkmcnt(0)
	ds_read2_b32 v[18:19], v24 offset0:33 offset1:41
	ds_read2_b32 v[26:27], v24 offset1:8
	ds_read2_b32 v[28:29], v24 offset0:66 offset1:74
	ds_read2_b32 v[30:31], v24 offset0:99 offset1:107
	ds_read2_b32 v[32:33], v24 offset0:132 offset1:140
	ds_read2_b32 v[34:35], v24 offset0:165 offset1:173
	ds_read2_b32 v[36:37], v24 offset0:198 offset1:206
	ds_read2_b32 v[38:39], v24 offset0:231 offset1:239
	v_ashrrev_i32_e32 v9, 31, v8
	v_lshl_add_u64 v[6:7], s[18:19], 1, v[4:5]
	v_lshlrev_b64 v[40:41], 11, v[8:9]
	s_waitcnt lgkmcnt(6)
	v_cvt_pk_bf16_f32 v14, v26, v18
	s_waitcnt lgkmcnt(4)
	v_cvt_pk_bf16_f32 v15, v28, v30
	s_waitcnt lgkmcnt(2)
	v_cvt_pk_bf16_f32 v16, v32, v34
	s_waitcnt lgkmcnt(0)
	v_cvt_pk_bf16_f32 v17, v36, v38
	v_lshl_add_u64 v[40:41], v[6:7], 0, v[40:41]
	v_add_u32_e32 v18, 8, v8
	global_store_dwordx4 v[40:41], v[14:17], off sc1
	v_add_u32_e32 v40, 16, v8
	v_ashrrev_i32_e32 v41, 31, v40
	v_cvt_pk_bf16_f32 v14, v27, v19
	v_ashrrev_i32_e32 v19, 31, v18
	v_lshlrev_b64 v[18:19], 11, v[18:19]
	v_cvt_pk_bf16_f32 v15, v29, v31
	v_cvt_pk_bf16_f32 v16, v33, v35
	v_cvt_pk_bf16_f32 v17, v37, v39
	v_lshl_add_u64 v[18:19], v[6:7], 0, v[18:19]
	global_store_dwordx4 v[18:19], v[14:17], off sc1
	ds_read2_b32 v[18:19], v24 offset0:49 offset1:57
	ds_read2_b32 v[26:27], v24 offset0:16 offset1:24
	ds_read2_b32 v[28:29], v24 offset0:82 offset1:90
	ds_read2_b32 v[30:31], v24 offset0:115 offset1:123
	ds_read2_b32 v[32:33], v24 offset0:148 offset1:156
	ds_read2_b32 v[34:35], v24 offset0:181 offset1:189
	ds_read2_b32 v[36:37], v24 offset0:214 offset1:222
	ds_read2_b32 v[38:39], v24 offset0:247 offset1:255
	v_add_u32_e32 v8, 24, v8
	v_lshlrev_b64 v[40:41], 11, v[40:41]
	v_ashrrev_i32_e32 v9, 31, v8
	s_waitcnt lgkmcnt(6)
	v_cvt_pk_bf16_f32 v14, v26, v18
	s_waitcnt lgkmcnt(4)
	v_cvt_pk_bf16_f32 v15, v28, v30
	s_waitcnt lgkmcnt(2)
	v_cvt_pk_bf16_f32 v16, v32, v34
	s_waitcnt lgkmcnt(0)
	v_cvt_pk_bf16_f32 v17, v36, v38
	v_lshl_add_u64 v[40:41], v[6:7], 0, v[40:41]
	v_lshlrev_b64 v[8:9], 11, v[8:9]
	global_store_dwordx4 v[40:41], v[14:17], off sc1
	v_lshl_add_u64 v[6:7], v[6:7], 0, v[8:9]
	s_nop 0
	v_cvt_pk_bf16_f32 v14, v27, v19
	v_cvt_pk_bf16_f32 v15, v29, v31
	v_cvt_pk_bf16_f32 v16, v33, v35
	v_cvt_pk_bf16_f32 v17, v37, v39
	global_store_dwordx4 v[6:7], v[14:17], off sc1
	s_waitcnt lgkmcnt(0)
	s_cbranch_execnz .LBB0_1029
	s_branch .LBB0_1028

.LBB0_1037:
	s_add_i32 s11, s11, s10
	v_add_u32_e32 v6, s11, v20
	s_ashr_i32 s19, s18, 31
	v_ashrrev_i32_e32 v7, 31, v6
	s_mov_b32 s57, s56
	v_lshl_add_u64 v[8:9], s[18:19], 1, v[4:5]
	v_lshlrev_b64 v[14:15], 11, v[6:7]
	s_mov_b32 s58, s56
	s_mov_b32 s59, s56
	v_mov_b64_e32 v[16:17], s[56:57]
	v_lshl_add_u64 v[14:15], v[8:9], 0, v[14:15]
	v_mov_b64_e32 v[18:19], s[58:59]
	global_store_dwordx4 v[14:15], v[16:19], off sc1
	v_add_u32_e32 v14, 8, v6
	v_ashrrev_i32_e32 v15, 31, v14
	v_lshlrev_b64 v[14:15], 11, v[14:15]
	v_lshl_add_u64 v[14:15], v[8:9], 0, v[14:15]
	global_store_dwordx4 v[14:15], v[16:19], off sc1
	v_add_u32_e32 v14, 16, v6
	v_add_u32_e32 v6, 24, v6
	v_ashrrev_i32_e32 v15, 31, v14
	v_ashrrev_i32_e32 v7, 31, v6
	v_lshlrev_b64 v[14:15], 11, v[14:15]
	v_lshlrev_b64 v[6:7], 11, v[6:7]
	v_lshl_add_u64 v[14:15], v[8:9], 0, v[14:15]
	v_lshl_add_u64 v[6:7], v[8:9], 0, v[6:7]
	global_store_dwordx4 v[14:15], v[16:19], off sc1
	global_store_dwordx4 v[6:7], v[16:19], off sc1

.LBB0_1039:
	s_ashr_i32 s11, s9, 31
	s_lshr_b32 s11, s11, 27
	s_add_i32 s11, s9, s11
	s_ashr_i32 s11, s11, 5
	s_lshl_b32 s18, s11, 6
	s_lshl_b32 s11, s11, 10
	s_andn2_b64 vcc, exec, s[14:15]
	s_sub_i32 s11, 0, s11
	s_cbranch_vccnz .LBB0_1041
	s_add_i32 s24, s10, s11
	v_or_b32_e32 v18, s18, v20
	s_ashr_i32 s25, s24, 31
	v_ashrrev_i32_e32 v19, 31, v18
	v_or_b32_e32 v14, 8, v18
	v_or_b32_e32 v26, 16, v18
	v_lshl_add_u64 v[46:47], s[24:25], 2, v[2:3]
	v_lshlrev_b64 v[6:7], 12, v[18:19]
	v_ashrrev_i32_e32 v15, 31, v14
	v_ashrrev_i32_e32 v27, 31, v26
	v_lshl_add_u64 v[6:7], v[46:47], 0, v[6:7]
	v_lshlrev_b64 v[14:15], 12, v[14:15]
	v_lshlrev_b64 v[26:27], 12, v[26:27]
	v_or_b32_e32 v30, 24, v18
	global_load_dwordx4 v[6:9], v[6:7], off nt
	v_lshl_add_u64 v[14:15], v[46:47], 0, v[14:15]
	v_lshl_add_u64 v[26:27], v[46:47], 0, v[26:27]
	v_ashrrev_i32_e32 v31, 31, v30
	v_or_b32_e32 v34, 32, v18
	global_load_dwordx4 v[14:17], v[14:15], off nt
	v_lshlrev_b64 v[30:31], 12, v[30:31]
	global_load_dwordx4 v[26:29], v[26:27], off nt
	v_ashrrev_i32_e32 v35, 31, v34
	v_lshl_add_u64 v[30:31], v[46:47], 0, v[30:31]
	v_lshlrev_b64 v[34:35], 12, v[34:35]
	v_or_b32_e32 v38, 40, v18
	global_load_dwordx4 v[30:33], v[30:31], off nt
	v_lshl_add_u64 v[34:35], v[46:47], 0, v[34:35]
	v_ashrrev_i32_e32 v39, 31, v38
	global_load_dwordx4 v[34:37], v[34:35], off nt
	v_lshlrev_b64 v[38:39], 12, v[38:39]
	v_or_b32_e32 v42, 48, v18
	v_lshl_add_u64 v[38:39], v[46:47], 0, v[38:39]
	v_ashrrev_i32_e32 v43, 31, v42
	global_load_dwordx4 v[38:41], v[38:39], off nt
	v_lshlrev_b64 v[42:43], 12, v[42:43]
	v_or_b32_e32 v18, 56, v18
	v_lshl_add_u64 v[42:43], v[46:47], 0, v[42:43]
	v_ashrrev_i32_e32 v19, 31, v18
	global_load_dwordx4 v[42:45], v[42:43], off nt
	v_lshlrev_b64 v[18:19], 12, v[18:19]
	v_lshl_add_u64 v[18:19], v[46:47], 0, v[18:19]
	global_load_dwordx4 v[46:49], v[18:19], off nt
	v_add_u32_e32 v0, v21, v23
	s_ashr_i32 s19, s18, 31
	s_waitcnt vmcnt(7)
	ds_write2_b32 v22, v6, v7 offset1:1
	ds_write2_b32 v22, v8, v9 offset0:2 offset1:3
	v_add_u32_e32 v6, 0x420, v0
	s_waitcnt vmcnt(6)
	ds_write2_b32 v0, v14, v15 offset1:1
	ds_write2_b32 v0, v16, v17 offset0:2 offset1:3
	s_waitcnt vmcnt(5)
	ds_write2_b32 v6, v26, v27 offset1:1
	v_add_u32_e32 v6, 0x428, v0
	ds_write2_b32 v6, v28, v29 offset1:1
	v_add_u32_e32 v6, 0x840, v0
	v_add_u32_e32 v0, 0x848, v0
	s_waitcnt vmcnt(4)
	ds_write2_b32 v0, v32, v33 offset1:1
	v_add_u32_e32 v0, 0x1080, v22
	ds_write2_b32 v6, v30, v31 offset1:1
	s_waitcnt vmcnt(3)
	ds_write2_b32 v0, v34, v35 offset1:1
	v_add_u32_e32 v0, 0x1088, v22
	ds_write2_b32 v0, v36, v37 offset1:1
	v_add_u32_e32 v0, 0x14a0, v22
	v_lshl_add_u64 v[6:7], s[18:19], 1, v[4:5]
	s_waitcnt vmcnt(2)
	ds_write2_b32 v0, v38, v39 offset1:1
	v_add_u32_e32 v0, 0x14a8, v22
	ds_write2_b32 v0, v40, v41 offset1:1
	v_add_u32_e32 v0, 0x18c0, v22
	v_add_u32_e32 v38, s24, v20
	s_waitcnt vmcnt(1)
	ds_write2_b32 v0, v42, v43 offset1:1
	v_add_u32_e32 v0, 0x18c8, v22
	ds_write2_b32 v0, v44, v45 offset1:1
	v_add_u32_e32 v0, 0x1ce0, v22
	s_waitcnt vmcnt(0)
	ds_write2_b32 v0, v46, v47 offset1:1
	v_add_u32_e32 v0, 0x1ce8, v22
	ds_write2_b32 v0, v48, v49 offset1:1
	s_waitcnt lgkmcnt(0)
	ds_read2_b32 v[8:9], v24 offset0:33 offset1:41
	ds_read2_b32 v[18:19], v24 offset1:8
	ds_read2_b32 v[26:27], v24 offset0:66 offset1:74
	ds_read2_b32 v[28:29], v24 offset0:99 offset1:107
	ds_read2_b32 v[30:31], v24 offset0:132 offset1:140
	ds_read2_b32 v[32:33], v24 offset0:165 offset1:173
	ds_read2_b32 v[34:35], v24 offset0:198 offset1:206
	ds_read2_b32 v[36:37], v24 offset0:231 offset1:239
	v_ashrrev_i32_e32 v39, 31, v38
	v_lshlrev_b64 v[40:41], 11, v[38:39]
	s_waitcnt lgkmcnt(6)
	v_cvt_pk_bf16_f32 v14, v18, v8
	s_waitcnt lgkmcnt(4)
	v_cvt_pk_bf16_f32 v15, v26, v28
	s_waitcnt lgkmcnt(2)
	v_cvt_pk_bf16_f32 v16, v30, v32
	s_waitcnt lgkmcnt(0)
	v_cvt_pk_bf16_f32 v17, v34, v36
	v_lshl_add_u64 v[40:41], v[6:7], 0, v[40:41]
	v_add_u32_e32 v8, 8, v38
	global_store_dwordx4 v[40:41], v[14:17], off sc1
	v_add_u32_e32 v40, 16, v38
	v_ashrrev_i32_e32 v41, 31, v40
	v_cvt_pk_bf16_f32 v14, v19, v9
	v_ashrrev_i32_e32 v9, 31, v8
	v_lshlrev_b64 v[8:9], 11, v[8:9]
	v_cvt_pk_bf16_f32 v15, v27, v29
	v_cvt_pk_bf16_f32 v16, v31, v33
	v_cvt_pk_bf16_f32 v17, v35, v37
	v_lshl_add_u64 v[8:9], v[6:7], 0, v[8:9]
	global_store_dwordx4 v[8:9], v[14:17], off sc1
	ds_read2_b32 v[8:9], v24 offset0:49 offset1:57
	ds_read2_b32 v[18:19], v24 offset0:16 offset1:24
	ds_read2_b32 v[26:27], v24 offset0:82 offset1:90
	ds_read2_b32 v[28:29], v24 offset0:115 offset1:123
	ds_read2_b32 v[30:31], v24 offset0:148 offset1:156
	ds_read2_b32 v[32:33], v24 offset0:181 offset1:189
	ds_read2_b32 v[34:35], v24 offset0:214 offset1:222
	ds_read2_b32 v[36:37], v24 offset0:247 offset1:255
	v_lshlrev_b64 v[40:41], 11, v[40:41]
	s_waitcnt lgkmcnt(6)
	v_cvt_pk_bf16_f32 v14, v18, v8
	s_waitcnt lgkmcnt(4)
	v_cvt_pk_bf16_f32 v15, v26, v28
	s_waitcnt lgkmcnt(2)
	v_cvt_pk_bf16_f32 v16, v30, v32
	s_waitcnt lgkmcnt(0)
	v_cvt_pk_bf16_f32 v17, v34, v36
	v_lshl_add_u64 v[40:41], v[6:7], 0, v[40:41]
	v_add_u32_e32 v8, 24, v38
	global_store_dwordx4 v[40:41], v[14:17], off sc1
	s_nop 1
	v_cvt_pk_bf16_f32 v14, v19, v9
	v_ashrrev_i32_e32 v9, 31, v8
	v_lshlrev_b64 v[8:9], 11, v[8:9]
	v_cvt_pk_bf16_f32 v15, v27, v29
	v_cvt_pk_bf16_f32 v16, v31, v33
	v_cvt_pk_bf16_f32 v17, v35, v37
	v_lshl_add_u64 v[6:7], v[6:7], 0, v[8:9]
	global_store_dwordx4 v[6:7], v[14:17], off sc1
	s_waitcnt lgkmcnt(0)
	s_cbranch_execnz .LBB0_1038
	s_branch .LBB0_1037

.LBB0_1048:
	s_add_i32 s12, s12, s10
	v_add_u32_e32 v6, s12, v0
	s_ashr_i32 s19, s18, 31
	v_ashrrev_i32_e32 v7, 31, v6
	s_mov_b32 s57, s56
	v_lshl_add_u64 v[8:9], s[18:19], 1, v[16:17]
	v_lshlrev_b64 v[14:15], 12, v[6:7]
	s_mov_b32 s58, s56
	s_mov_b32 s59, s56
	v_mov_b64_e32 v[26:27], s[56:57]
	v_lshl_add_u64 v[14:15], v[8:9], 0, v[14:15]
	v_mov_b64_e32 v[28:29], s[58:59]
	global_store_dwordx4 v[14:15], v[26:29], off sc1
	v_add_u32_e32 v14, 8, v6
	v_ashrrev_i32_e32 v15, 31, v14
	v_lshlrev_b64 v[14:15], 12, v[14:15]
	v_lshl_add_u64 v[14:15], v[8:9], 0, v[14:15]
	global_store_dwordx4 v[14:15], v[26:29], off sc1
	v_add_u32_e32 v14, 16, v6
	v_add_u32_e32 v6, 24, v6
	v_ashrrev_i32_e32 v15, 31, v14
	v_ashrrev_i32_e32 v7, 31, v6
	v_lshlrev_b64 v[14:15], 12, v[14:15]
	v_lshlrev_b64 v[6:7], 12, v[6:7]
	v_lshl_add_u64 v[14:15], v[8:9], 0, v[14:15]
	v_lshl_add_u64 v[6:7], v[8:9], 0, v[6:7]
	global_store_dwordx4 v[14:15], v[26:29], off sc1
	global_store_dwordx4 v[6:7], v[26:29], off sc1

.LBB0_1050:
	s_ashr_i32 s12, s11, 31
	s_lshr_b32 s12, s12, 27
	s_add_i32 s12, s11, s12
	s_ashr_i32 s12, s12, 5
	s_lshl_b32 s18, s12, 6
	s_lshl_b32 s12, s12, 10
	s_andn2_b64 vcc, exec, s[14:15]
	s_sub_i32 s12, 0, s12
	s_cbranch_vccnz .LBB0_1052
	s_add_i32 s24, s10, s12
	v_or_b32_e32 v14, s18, v20
	s_ashr_i32 s25, s24, 31
	v_ashrrev_i32_e32 v15, 31, v14
	v_lshl_add_u64 v[18:19], s[24:25], 2, v[4:5]
	v_lshlrev_b64 v[6:7], 12, v[14:15]
	v_or_b32_e32 v26, 8, v14
	v_or_b32_e32 v30, 16, v14
	v_lshl_add_u64 v[6:7], v[18:19], 0, v[6:7]
	v_ashrrev_i32_e32 v27, 31, v26
	v_ashrrev_i32_e32 v31, 31, v30
	global_load_dwordx4 v[6:9], v[6:7], off nt
	v_lshlrev_b64 v[26:27], 12, v[26:27]
	v_lshlrev_b64 v[30:31], 12, v[30:31]
	v_or_b32_e32 v34, 24, v14
	v_lshl_add_u64 v[26:27], v[18:19], 0, v[26:27]
	v_lshl_add_u64 v[30:31], v[18:19], 0, v[30:31]
	v_ashrrev_i32_e32 v35, 31, v34
	v_or_b32_e32 v38, 32, v14
	global_load_dwordx4 v[26:29], v[26:27], off nt
	v_lshlrev_b64 v[34:35], 12, v[34:35]
	global_load_dwordx4 v[30:33], v[30:31], off nt
	v_ashrrev_i32_e32 v39, 31, v38
	v_lshl_add_u64 v[34:35], v[18:19], 0, v[34:35]
	v_lshlrev_b64 v[38:39], 12, v[38:39]
	v_or_b32_e32 v42, 40, v14
	global_load_dwordx4 v[34:37], v[34:35], off nt
	v_lshl_add_u64 v[38:39], v[18:19], 0, v[38:39]
	v_ashrrev_i32_e32 v43, 31, v42
	global_load_dwordx4 v[38:41], v[38:39], off nt
	v_lshlrev_b64 v[42:43], 12, v[42:43]
	v_or_b32_e32 v46, 48, v14
	v_lshl_add_u64 v[42:43], v[18:19], 0, v[42:43]
	v_ashrrev_i32_e32 v47, 31, v46
	global_load_dwordx4 v[42:45], v[42:43], off nt
	v_lshlrev_b64 v[46:47], 12, v[46:47]
	v_or_b32_e32 v14, 56, v14
	v_lshl_add_u64 v[46:47], v[18:19], 0, v[46:47]
	v_ashrrev_i32_e32 v15, 31, v14
	global_load_dwordx4 v[46:49], v[46:47], off nt
	v_lshlrev_b64 v[14:15], 12, v[14:15]
	v_lshl_add_u64 v[14:15], v[18:19], 0, v[14:15]
	global_load_dwordx4 v[50:53], v[14:15], off nt
	s_ashr_i32 s19, s18, 31
	s_waitcnt vmcnt(7)
	ds_write2_b32 v22, v6, v7 offset1:1
	ds_write2_b32 v22, v8, v9 offset0:2 offset1:3
	v_add_u32_e32 v6, v21, v23
	v_add_u32_e32 v7, 0x420, v6
	s_waitcnt vmcnt(6)
	ds_write2_b32 v6, v26, v27 offset1:1
	ds_write2_b32 v6, v28, v29 offset0:2 offset1:3
	s_waitcnt vmcnt(5)
	ds_write2_b32 v7, v30, v31 offset1:1
	v_add_u32_e32 v7, 0x428, v6
	ds_write2_b32 v7, v32, v33 offset1:1
	v_add_u32_e32 v7, 0x840, v6
	v_add_u32_e32 v6, 0x848, v6
	s_waitcnt vmcnt(4)
	ds_write2_b32 v6, v36, v37 offset1:1
	v_add_u32_e32 v6, 0x1080, v22
	ds_write2_b32 v7, v34, v35 offset1:1
	s_waitcnt vmcnt(3)
	ds_write2_b32 v6, v38, v39 offset1:1
	v_add_u32_e32 v6, 0x1088, v22
	ds_write2_b32 v6, v40, v41 offset1:1
	v_add_u32_e32 v6, 0x14a0, v22
	v_add_u32_e32 v40, s24, v0
	s_waitcnt vmcnt(2)
	ds_write2_b32 v6, v42, v43 offset1:1
	v_add_u32_e32 v6, 0x14a8, v22
	ds_write2_b32 v6, v44, v45 offset1:1
	v_add_u32_e32 v6, 0x18c0, v22
	v_ashrrev_i32_e32 v41, 31, v40
	s_waitcnt vmcnt(1)
	ds_write2_b32 v6, v46, v47 offset1:1
	v_add_u32_e32 v6, 0x18c8, v22
	ds_write2_b32 v6, v48, v49 offset1:1
	v_add_u32_e32 v6, 0x1ce0, v22
	s_waitcnt vmcnt(0)
	ds_write2_b32 v6, v50, v51 offset1:1
	v_add_u32_e32 v6, 0x1ce8, v22
	ds_write2_b32 v6, v52, v53 offset1:1
	s_waitcnt lgkmcnt(0)
	ds_read2_b32 v[8:9], v24 offset0:33 offset1:41
	ds_read2_b32 v[14:15], v24 offset1:8
	ds_read2_b32 v[18:19], v24 offset0:66 offset1:74
	ds_read2_b32 v[30:31], v24 offset0:99 offset1:107
	ds_read2_b32 v[32:33], v24 offset0:132 offset1:140
	ds_read2_b32 v[34:35], v24 offset0:165 offset1:173
	ds_read2_b32 v[36:37], v24 offset0:198 offset1:206
	ds_read2_b32 v[38:39], v24 offset0:231 offset1:239
	v_lshl_add_u64 v[6:7], s[18:19], 1, v[16:17]
	v_lshlrev_b64 v[42:43], 12, v[40:41]
	s_waitcnt lgkmcnt(6)
	v_cvt_pk_bf16_f32 v26, v14, v8
	s_waitcnt lgkmcnt(4)
	v_cvt_pk_bf16_f32 v27, v18, v30
	s_waitcnt lgkmcnt(2)
	v_cvt_pk_bf16_f32 v28, v32, v34
	s_waitcnt lgkmcnt(0)
	v_cvt_pk_bf16_f32 v29, v36, v38
	v_lshl_add_u64 v[42:43], v[6:7], 0, v[42:43]
	v_add_u32_e32 v8, 8, v40
	global_store_dwordx4 v[42:43], v[26:29], off sc1
	v_add_u32_e32 v42, 16, v40
	v_ashrrev_i32_e32 v43, 31, v42
	v_cvt_pk_bf16_f32 v26, v15, v9
	v_ashrrev_i32_e32 v9, 31, v8
	v_lshlrev_b64 v[8:9], 12, v[8:9]
	v_cvt_pk_bf16_f32 v27, v19, v31
	v_cvt_pk_bf16_f32 v28, v33, v35
	v_cvt_pk_bf16_f32 v29, v37, v39
	v_lshl_add_u64 v[8:9], v[6:7], 0, v[8:9]
	global_store_dwordx4 v[8:9], v[26:29], off sc1
	ds_read2_b32 v[8:9], v24 offset0:49 offset1:57
	ds_read2_b32 v[14:15], v24 offset0:16 offset1:24
	ds_read2_b32 v[18:19], v24 offset0:82 offset1:90
	ds_read2_b32 v[30:31], v24 offset0:115 offset1:123
	ds_read2_b32 v[32:33], v24 offset0:148 offset1:156
	ds_read2_b32 v[34:35], v24 offset0:181 offset1:189
	ds_read2_b32 v[36:37], v24 offset0:214 offset1:222
	ds_read2_b32 v[38:39], v24 offset0:247 offset1:255
	v_lshlrev_b64 v[42:43], 12, v[42:43]
	s_waitcnt lgkmcnt(6)
	v_cvt_pk_bf16_f32 v26, v14, v8
	s_waitcnt lgkmcnt(4)
	v_cvt_pk_bf16_f32 v27, v18, v30
	s_waitcnt lgkmcnt(2)
	v_cvt_pk_bf16_f32 v28, v32, v34
	s_waitcnt lgkmcnt(0)
	v_cvt_pk_bf16_f32 v29, v36, v38
	v_lshl_add_u64 v[42:43], v[6:7], 0, v[42:43]
	v_add_u32_e32 v8, 24, v40
	global_store_dwordx4 v[42:43], v[26:29], off sc1
	s_nop 1
	v_cvt_pk_bf16_f32 v26, v15, v9
	v_ashrrev_i32_e32 v9, 31, v8
	v_lshlrev_b64 v[8:9], 12, v[8:9]
	v_cvt_pk_bf16_f32 v27, v19, v31
	v_cvt_pk_bf16_f32 v28, v33, v35
	v_cvt_pk_bf16_f32 v29, v37, v39
	v_lshl_add_u64 v[6:7], v[6:7], 0, v[8:9]
	global_store_dwordx4 v[6:7], v[26:29], off sc1
	s_waitcnt lgkmcnt(0)
	s_cbranch_execnz .LBB0_1049
	s_branch .LBB0_1048

.LBB0_1057:
	s_add_i32 s13, s13, s12
	v_add_u32_e32 v8, s13, v13
	v_add_u32_e32 v0, 0xc00, v8
	s_ashr_i32 s37, s36, 31
	s_mov_b32 s57, s56
	v_lshl_add_u64 v[4:5], s[36:37], 1, v[16:17]
	v_lshlrev_b64 v[6:7], 12, v[0:1]
	s_mov_b32 s58, s56
	s_mov_b32 s59, s56
	v_mov_b64_e32 v[34:35], s[56:57]
	v_lshl_add_u64 v[6:7], v[4:5], 0, v[6:7]
	v_mov_b64_e32 v[36:37], s[58:59]
	v_add_u32_e32 v0, 0xc08, v8
	global_store_dwordx4 v[6:7], v[34:37], off sc1
	v_lshlrev_b64 v[6:7], 12, v[0:1]
	v_lshl_add_u64 v[6:7], v[4:5], 0, v[6:7]
	v_add_u32_e32 v0, 0xc10, v8
	global_store_dwordx4 v[6:7], v[34:37], off sc1
	v_lshlrev_b64 v[6:7], 12, v[0:1]
	v_lshl_add_u64 v[6:7], v[4:5], 0, v[6:7]
	v_add_u32_e32 v0, 0xc18, v8
	global_store_dwordx4 v[6:7], v[34:37], off sc1
	v_lshlrev_b64 v[6:7], 12, v[0:1]
	v_lshl_add_u64 v[4:5], v[4:5], 0, v[6:7]
	global_store_dwordx4 v[4:5], v[34:37], off sc1

.LBB0_1059:
	s_lshr_b32 s13, s11, 31
	s_add_i32 s13, s11, s13
	s_lshl_b32 s13, s13, 5
	s_and_b32 s36, s13, 0xffffffc0
	s_andn2_b64 vcc, exec, s[18:19]
	s_sub_i32 s13, 0, s36
	s_cbranch_vccnz .LBB0_1061
	s_add_i32 s38, s12, s13
	v_or_b32_e32 v8, s36, v20
	s_ashr_i32 s39, s38, 31
	v_ashrrev_i32_e32 v9, 31, v8
	v_or_b32_e32 v34, 8, v8
	v_or_b32_e32 v38, 16, v8
	v_lshl_add_u64 v[18:19], s[38:39], 2, v[2:3]
	v_lshlrev_b64 v[4:5], 8, v[8:9]
	v_ashrrev_i32_e32 v35, 31, v34
	v_ashrrev_i32_e32 v39, 31, v38
	v_lshl_add_u64 v[4:5], v[18:19], 0, v[4:5]
	v_lshlrev_b64 v[34:35], 8, v[34:35]
	v_lshlrev_b64 v[38:39], 8, v[38:39]
	v_or_b32_e32 v42, 24, v8
	global_load_dwordx4 v[4:7], v[4:5], off nt
	v_lshl_add_u64 v[34:35], v[18:19], 0, v[34:35]
	v_lshl_add_u64 v[38:39], v[18:19], 0, v[38:39]
	v_ashrrev_i32_e32 v43, 31, v42
	v_or_b32_e32 v46, 32, v8
	global_load_dwordx4 v[34:37], v[34:35], off nt
	v_lshlrev_b64 v[42:43], 8, v[42:43]
	global_load_dwordx4 v[38:41], v[38:39], off nt
	v_ashrrev_i32_e32 v47, 31, v46
	v_lshl_add_u64 v[42:43], v[18:19], 0, v[42:43]
	v_lshlrev_b64 v[46:47], 8, v[46:47]
	v_or_b32_e32 v50, 40, v8
	global_load_dwordx4 v[42:45], v[42:43], off nt
	v_lshl_add_u64 v[46:47], v[18:19], 0, v[46:47]
	v_ashrrev_i32_e32 v51, 31, v50
	global_load_dwordx4 v[46:49], v[46:47], off nt
	v_lshlrev_b64 v[50:51], 8, v[50:51]
	v_or_b32_e32 v54, 48, v8
	v_lshl_add_u64 v[50:51], v[18:19], 0, v[50:51]
	v_ashrrev_i32_e32 v55, 31, v54
	global_load_dwordx4 v[50:53], v[50:51], off nt
	v_lshlrev_b64 v[54:55], 8, v[54:55]
	v_or_b32_e32 v8, 56, v8
	v_lshl_add_u64 v[54:55], v[18:19], 0, v[54:55]
	v_ashrrev_i32_e32 v9, 31, v8
	global_load_dwordx4 v[54:57], v[54:55], off nt
	v_lshlrev_b64 v[8:9], 8, v[8:9]
	v_lshl_add_u64 v[8:9], v[18:19], 0, v[8:9]
	global_load_dwordx4 v[58:61], v[8:9], off nt
	v_add_u32_e32 v0, v21, v23
	v_add_u32_e32 v11, s38, v13
	s_ashr_i32 s37, s36, 31
	s_waitcnt vmcnt(7)
	ds_write2_b32 v22, v4, v5 offset1:1
	ds_write2_b32 v22, v6, v7 offset0:2 offset1:3
	v_add_u32_e32 v4, 0x420, v0
	s_waitcnt vmcnt(6)
	ds_write2_b32 v0, v34, v35 offset1:1
	ds_write2_b32 v0, v36, v37 offset0:2 offset1:3
	s_waitcnt vmcnt(5)
	ds_write2_b32 v4, v38, v39 offset1:1
	v_add_u32_e32 v4, 0x428, v0
	ds_write2_b32 v4, v40, v41 offset1:1
	v_add_u32_e32 v4, 0x840, v0
	v_add_u32_e32 v0, 0x848, v0
	s_waitcnt vmcnt(4)
	ds_write2_b32 v0, v44, v45 offset1:1
	v_add_u32_e32 v0, 0x1080, v22
	ds_write2_b32 v4, v42, v43 offset1:1
	s_waitcnt vmcnt(3)
	ds_write2_b32 v0, v46, v47 offset1:1
	v_add_u32_e32 v0, 0x1088, v22
	ds_write2_b32 v0, v48, v49 offset1:1
	v_add_u32_e32 v0, 0x14a0, v22
	v_lshl_add_u64 v[4:5], s[36:37], 1, v[16:17]
	s_waitcnt vmcnt(2)
	ds_write2_b32 v0, v50, v51 offset1:1
	v_add_u32_e32 v0, 0x14a8, v22
	ds_write2_b32 v0, v52, v53 offset1:1
	v_add_u32_e32 v0, 0x18c0, v22
	s_waitcnt vmcnt(1)
	ds_write2_b32 v0, v54, v55 offset1:1
	v_add_u32_e32 v0, 0x18c8, v22
	ds_write2_b32 v0, v56, v57 offset1:1
	v_add_u32_e32 v0, 0x1ce0, v22
	s_waitcnt vmcnt(0)
	ds_write2_b32 v0, v58, v59 offset1:1
	v_add_u32_e32 v0, 0x1ce8, v22
	ds_write2_b32 v0, v60, v61 offset1:1
	s_waitcnt lgkmcnt(0)
	ds_read2_b32 v[18:19], v24 offset0:33 offset1:41
	ds_read2_b32 v[34:35], v24 offset1:8
	ds_read2_b32 v[36:37], v24 offset0:66 offset1:74
	ds_read2_b32 v[38:39], v24 offset0:99 offset1:107
	ds_read2_b32 v[40:41], v24 offset0:132 offset1:140
	ds_read2_b32 v[42:43], v24 offset0:165 offset1:173
	ds_read2_b32 v[44:45], v24 offset0:198 offset1:206
	ds_read2_b32 v[46:47], v24 offset0:231 offset1:239
	v_add_u32_e32 v0, 0xc00, v11
	v_lshlrev_b64 v[48:49], 12, v[0:1]
	s_waitcnt lgkmcnt(6)
	v_cvt_pk_bf16_f32 v6, v34, v18
	s_waitcnt lgkmcnt(4)
	v_cvt_pk_bf16_f32 v7, v36, v38
	s_waitcnt lgkmcnt(2)
	v_cvt_pk_bf16_f32 v8, v40, v42
	s_waitcnt lgkmcnt(0)
	v_cvt_pk_bf16_f32 v9, v44, v46
	v_lshl_add_u64 v[48:49], v[4:5], 0, v[48:49]
	v_add_u32_e32 v0, 0xc08, v11
	global_store_dwordx4 v[48:49], v[6:9], off sc1
	s_nop 1
	v_cvt_pk_bf16_f32 v6, v35, v19
	v_lshlrev_b64 v[18:19], 12, v[0:1]
	v_cvt_pk_bf16_f32 v7, v37, v39
	v_cvt_pk_bf16_f32 v8, v41, v43
	v_cvt_pk_bf16_f32 v9, v45, v47
	v_lshl_add_u64 v[18:19], v[4:5], 0, v[18:19]
	global_store_dwordx4 v[18:19], v[6:9], off sc1
	ds_read2_b32 v[18:19], v24 offset0:49 offset1:57
	ds_read2_b32 v[34:35], v24 offset0:16 offset1:24
	ds_read2_b32 v[36:37], v24 offset0:82 offset1:90
	ds_read2_b32 v[38:39], v24 offset0:115 offset1:123
	ds_read2_b32 v[40:41], v24 offset0:148 offset1:156
	ds_read2_b32 v[42:43], v24 offset0:181 offset1:189
	ds_read2_b32 v[44:45], v24 offset0:214 offset1:222
	ds_read2_b32 v[46:47], v24 offset0:247 offset1:255
	v_add_u32_e32 v0, 0xc10, v11
	v_lshlrev_b64 v[48:49], 12, v[0:1]
	s_waitcnt lgkmcnt(6)
	v_cvt_pk_bf16_f32 v6, v34, v18
	s_waitcnt lgkmcnt(4)
	v_cvt_pk_bf16_f32 v7, v36, v38
	s_waitcnt lgkmcnt(2)
	v_cvt_pk_bf16_f32 v8, v40, v42
	s_waitcnt lgkmcnt(0)
	v_cvt_pk_bf16_f32 v9, v44, v46
	v_lshl_add_u64 v[48:49], v[4:5], 0, v[48:49]
	v_add_u32_e32 v0, 0xc18, v11
	global_store_dwordx4 v[48:49], v[6:9], off sc1
	s_nop 1
	v_cvt_pk_bf16_f32 v6, v35, v19
	v_lshlrev_b64 v[18:19], 12, v[0:1]
	v_cvt_pk_bf16_f32 v7, v37, v39
	v_cvt_pk_bf16_f32 v8, v41, v43
	v_cvt_pk_bf16_f32 v9, v45, v47
	v_lshl_add_u64 v[4:5], v[4:5], 0, v[18:19]
	global_store_dwordx4 v[4:5], v[6:9], off sc1
	s_waitcnt lgkmcnt(0)
	s_cbranch_execnz .LBB0_1058
	s_branch .LBB0_1057

.LBB0_1064:
	s_add_i32 s13, s13, s12
	v_add_u32_e32 v6, s13, v13
	v_add_u32_e32 v0, 0xc00, v6
	s_ashr_i32 s35, s34, 31
	s_mov_b32 s57, s56
	v_lshl_add_u64 v[2:3], s[34:35], 1, v[14:15]
	v_lshlrev_b64 v[4:5], 12, v[0:1]
	s_mov_b32 s58, s56
	s_mov_b32 s59, s56
	v_mov_b64_e32 v[34:35], s[56:57]
	v_lshl_add_u64 v[4:5], v[2:3], 0, v[4:5]
	v_mov_b64_e32 v[36:37], s[58:59]
	v_add_u32_e32 v0, 0xc08, v6
	global_store_dwordx4 v[4:5], v[34:37], off sc1
	v_lshlrev_b64 v[4:5], 12, v[0:1]
	v_lshl_add_u64 v[4:5], v[2:3], 0, v[4:5]
	v_add_u32_e32 v0, 0xc10, v6
	global_store_dwordx4 v[4:5], v[34:37], off sc1
	v_lshlrev_b64 v[4:5], 12, v[0:1]
	v_lshl_add_u64 v[4:5], v[2:3], 0, v[4:5]
	v_add_u32_e32 v0, 0xc18, v6
	global_store_dwordx4 v[4:5], v[34:37], off sc1
	v_lshlrev_b64 v[4:5], 12, v[0:1]
	v_lshl_add_u64 v[2:3], v[2:3], 0, v[4:5]
	global_store_dwordx4 v[2:3], v[34:37], off sc1

.LBB0_1066:
	s_lshr_b32 s13, s11, 31
	s_add_i32 s13, s11, s13
	s_lshl_b32 s13, s13, 5
	s_and_b32 s34, s13, 0xffffffc0
	s_andn2_b64 vcc, exec, s[18:19]
	s_sub_i32 s13, 0, s34
	s_cbranch_vccnz .LBB0_1068
	s_add_i32 s36, s12, s13
	v_or_b32_e32 v58, s34, v20
	s_ashr_i32 s37, s36, 31
	v_ashrrev_i32_e32 v59, 31, v58
	v_lshl_add_u64 v[2:3], s[36:37], 2, v[18:19]
	v_lshlrev_b64 v[4:5], 8, v[58:59]
	v_lshl_add_u64 v[4:5], v[2:3], 0, v[4:5]
	global_load_dwordx4 v[34:37], v[4:5], off nt
	v_or_b32_e32 v4, 8, v58
	v_ashrrev_i32_e32 v5, 31, v4
	v_lshlrev_b64 v[4:5], 8, v[4:5]
	v_lshl_add_u64 v[4:5], v[2:3], 0, v[4:5]
	global_load_dwordx4 v[38:41], v[4:5], off nt
	v_or_b32_e32 v4, 16, v58
	v_ashrrev_i32_e32 v5, 31, v4
	v_lshlrev_b64 v[4:5], 8, v[4:5]
	v_lshl_add_u64 v[4:5], v[2:3], 0, v[4:5]
	global_load_dwordx4 v[42:45], v[4:5], off nt
	v_or_b32_e32 v4, 24, v58
	v_ashrrev_i32_e32 v5, 31, v4
	v_lshlrev_b64 v[4:5], 8, v[4:5]
	v_lshl_add_u64 v[4:5], v[2:3], 0, v[4:5]
	global_load_dwordx4 v[46:49], v[4:5], off nt
	v_or_b32_e32 v4, 32, v58
	v_ashrrev_i32_e32 v5, 31, v4
	v_lshlrev_b64 v[4:5], 8, v[4:5]
	v_lshl_add_u64 v[4:5], v[2:3], 0, v[4:5]
	global_load_dwordx4 v[50:53], v[4:5], off nt
	v_or_b32_e32 v4, 40, v58
	v_ashrrev_i32_e32 v5, 31, v4
	v_lshlrev_b64 v[4:5], 8, v[4:5]
	v_lshl_add_u64 v[4:5], v[2:3], 0, v[4:5]
	global_load_dwordx4 v[54:57], v[4:5], off nt
	v_or_b32_e32 v4, 48, v58
	v_ashrrev_i32_e32 v5, 31, v4
	v_lshlrev_b64 v[4:5], 8, v[4:5]
	v_lshl_add_u64 v[4:5], v[2:3], 0, v[4:5]
	global_load_dwordx4 v[6:9], v[4:5], off nt
	v_or_b32_e32 v4, 56, v58
	v_lshl_add_u64 v[58:59], v[58:59], 2, s[24:25]
	global_load_dword v0, v[58:59], off
	v_ashrrev_i32_e32 v5, 31, v4
	v_lshlrev_b64 v[4:5], 8, v[4:5]
	v_lshl_add_u64 v[2:3], v[2:3], 0, v[4:5]
	global_load_dwordx4 v[2:5], v[2:3], off nt
	v_add_u32_e32 v11, v21, v23
	s_ashr_i32 s35, s34, 31
	s_waitcnt vmcnt(1)
	v_pk_mul_f32 v[34:35], v[34:35], v[0:1] op_sel_hi:[1,0]
	v_pk_mul_f32 v[36:37], v[36:37], v[0:1] op_sel_hi:[1,0]
	ds_write2_b32 v22, v34, v35 offset1:1
	ds_write2_b32 v22, v36, v37 offset0:2 offset1:3
	v_or_b32_e32 v34, s34, v26
	v_ashrrev_i32_e32 v35, 31, v34
	v_lshl_add_u64 v[34:35], v[34:35], 2, s[24:25]
	global_load_dword v0, v[34:35], off
	s_waitcnt vmcnt(0)
	v_pk_mul_f32 v[34:35], v[40:41], v[0:1] op_sel_hi:[1,0]
	v_pk_mul_f32 v[36:37], v[38:39], v[0:1] op_sel_hi:[1,0]
	ds_write2_b32 v11, v36, v37 offset1:1
	ds_write2_b32 v11, v34, v35 offset0:2 offset1:3
	v_or_b32_e32 v34, s34, v27
	v_ashrrev_i32_e32 v35, 31, v34
	v_lshl_add_u64 v[34:35], v[34:35], 2, s[24:25]
	global_load_dword v0, v[34:35], off
	s_waitcnt vmcnt(0)
	v_pk_mul_f32 v[34:35], v[44:45], v[0:1] op_sel_hi:[1,0]
	v_pk_mul_f32 v[36:37], v[42:43], v[0:1] op_sel_hi:[1,0]
	v_add_u32_e32 v0, 0x420, v11
	ds_write2_b32 v0, v36, v37 offset1:1
	v_add_u32_e32 v0, 0x428, v11
	ds_write2_b32 v0, v34, v35 offset1:1
	v_or_b32_e32 v34, s34, v25
	v_ashrrev_i32_e32 v35, 31, v34
	v_lshl_add_u64 v[34:35], v[34:35], 2, s[24:25]
	global_load_dword v0, v[34:35], off
	s_waitcnt vmcnt(0)
	v_pk_mul_f32 v[34:35], v[48:49], v[0:1] op_sel_hi:[1,0]
	v_pk_mul_f32 v[36:37], v[46:47], v[0:1] op_sel_hi:[1,0]
	v_add_u32_e32 v0, 0x840, v11
	ds_write2_b32 v0, v36, v37 offset1:1
	v_add_u32_e32 v0, 0x848, v11
	ds_write2_b32 v0, v34, v35 offset1:1
	v_or_b32_e32 v34, s34, v28
	v_ashrrev_i32_e32 v35, 31, v34
	v_lshl_add_u64 v[34:35], v[34:35], 2, s[24:25]
	global_load_dword v0, v[34:35], off
	v_add_u32_e32 v11, v21, v29
	s_waitcnt vmcnt(0)
	v_pk_mul_f32 v[34:35], v[52:53], v[0:1] op_sel_hi:[1,0]
	v_pk_mul_f32 v[36:37], v[50:51], v[0:1] op_sel_hi:[1,0]
	ds_write2_b32 v11, v36, v37 offset1:1
	ds_write2_b32 v11, v34, v35 offset0:2 offset1:3
	v_or_b32_e32 v34, s34, v30
	v_ashrrev_i32_e32 v35, 31, v34
	v_lshl_add_u64 v[34:35], v[34:35], 2, s[24:25]
	global_load_dword v0, v[34:35], off
	s_waitcnt vmcnt(0)
	v_pk_mul_f32 v[34:35], v[56:57], v[0:1] op_sel_hi:[1,0]
	v_pk_mul_f32 v[36:37], v[54:55], v[0:1] op_sel_hi:[1,0]
	v_add_u32_e32 v0, 0x420, v11
	ds_write2_b32 v0, v36, v37 offset1:1
	v_add_u32_e32 v0, 0x428, v11
	ds_write2_b32 v0, v34, v35 offset1:1
	v_or_b32_e32 v34, s34, v31
	v_ashrrev_i32_e32 v35, 31, v34
	v_lshl_add_u64 v[34:35], v[34:35], 2, s[24:25]
	global_load_dword v0, v[34:35], off
	s_waitcnt vmcnt(0)
	v_pk_mul_f32 v[8:9], v[8:9], v[0:1] op_sel_hi:[1,0]
	v_pk_mul_f32 v[6:7], v[6:7], v[0:1] op_sel_hi:[1,0]
	v_add_u32_e32 v0, 0x840, v11
	ds_write2_b32 v0, v6, v7 offset1:1
	v_or_b32_e32 v6, s34, v32
	v_ashrrev_i32_e32 v7, 31, v6
	v_add_u32_e32 v0, 0x848, v11
	v_lshl_add_u64 v[6:7], v[6:7], 2, s[24:25]
	ds_write2_b32 v0, v8, v9 offset1:1
	global_load_dword v0, v[6:7], off
	v_lshl_add_u64 v[6:7], s[34:35], 1, v[14:15]
	s_waitcnt vmcnt(0)
	v_pk_mul_f32 v[4:5], v[4:5], v[0:1] op_sel_hi:[1,0]
	v_pk_mul_f32 v[2:3], v[2:3], v[0:1] op_sel_hi:[1,0]
	v_add_u32_e32 v0, 0xc60, v11
	ds_write2_b32 v0, v2, v3 offset1:1
	v_add_u32_e32 v0, 0xc68, v11
	ds_write2_b32 v0, v4, v5 offset1:1
	s_waitcnt lgkmcnt(0)
	ds_read2_b32 v[8:9], v24 offset0:33 offset1:41
	ds_read2_b32 v[34:35], v24 offset1:8
	ds_read2_b32 v[36:37], v24 offset0:66 offset1:74
	ds_read2_b32 v[38:39], v24 offset0:99 offset1:107
	ds_read2_b32 v[40:41], v24 offset0:132 offset1:140
	ds_read2_b32 v[42:43], v24 offset0:165 offset1:173
	ds_read2_b32 v[44:45], v24 offset0:198 offset1:206
	ds_read2_b32 v[46:47], v24 offset0:231 offset1:239
	v_add_u32_e32 v11, s36, v13
	v_add_u32_e32 v0, 0xc00, v11
	v_lshlrev_b64 v[48:49], 12, v[0:1]
	s_waitcnt lgkmcnt(6)
	v_cvt_pk_bf16_f32 v2, v34, v8
	s_waitcnt lgkmcnt(4)
	v_cvt_pk_bf16_f32 v3, v36, v38
	s_waitcnt lgkmcnt(2)
	v_cvt_pk_bf16_f32 v4, v40, v42
	s_waitcnt lgkmcnt(0)
	v_cvt_pk_bf16_f32 v5, v44, v46
	v_lshl_add_u64 v[48:49], v[6:7], 0, v[48:49]
	v_add_u32_e32 v0, 0xc08, v11
	global_store_dwordx4 v[48:49], v[2:5], off sc1
	s_nop 1
	v_cvt_pk_bf16_f32 v2, v35, v9
	v_lshlrev_b64 v[8:9], 12, v[0:1]
	v_cvt_pk_bf16_f32 v3, v37, v39
	v_cvt_pk_bf16_f32 v4, v41, v43
	v_cvt_pk_bf16_f32 v5, v45, v47
	v_lshl_add_u64 v[8:9], v[6:7], 0, v[8:9]
	global_store_dwordx4 v[8:9], v[2:5], off sc1
	ds_read2_b32 v[8:9], v24 offset0:49 offset1:57
	ds_read2_b32 v[34:35], v24 offset0:16 offset1:24
	ds_read2_b32 v[36:37], v24 offset0:82 offset1:90
	ds_read2_b32 v[38:39], v24 offset0:115 offset1:123
	ds_read2_b32 v[40:41], v24 offset0:148 offset1:156
	ds_read2_b32 v[42:43], v24 offset0:181 offset1:189
	ds_read2_b32 v[44:45], v24 offset0:214 offset1:222
	ds_read2_b32 v[46:47], v24 offset0:247 offset1:255
	v_add_u32_e32 v0, 0xc10, v11
	v_lshlrev_b64 v[48:49], 12, v[0:1]
	s_waitcnt lgkmcnt(6)
	v_cvt_pk_bf16_f32 v2, v34, v8
	s_waitcnt lgkmcnt(4)
	v_cvt_pk_bf16_f32 v3, v36, v38
	s_waitcnt lgkmcnt(2)
	v_cvt_pk_bf16_f32 v4, v40, v42
	s_waitcnt lgkmcnt(0)
	v_cvt_pk_bf16_f32 v5, v44, v46
	v_lshl_add_u64 v[48:49], v[6:7], 0, v[48:49]
	v_add_u32_e32 v0, 0xc18, v11
	global_store_dwordx4 v[48:49], v[2:5], off sc1
	s_nop 1
	v_cvt_pk_bf16_f32 v2, v35, v9
	v_lshlrev_b64 v[8:9], 12, v[0:1]
	v_cvt_pk_bf16_f32 v3, v37, v39
	v_cvt_pk_bf16_f32 v4, v41, v43
	v_cvt_pk_bf16_f32 v5, v45, v47
	v_lshl_add_u64 v[6:7], v[6:7], 0, v[8:9]
	global_store_dwordx4 v[6:7], v[2:5], off sc1
	s_waitcnt lgkmcnt(0)
	s_cbranch_execnz .LBB0_1065
	s_branch .LBB0_1064

.LBB0_1071:
	s_add_i32 s13, s13, s12
	v_add_u32_e32 v8, s13, v13
	v_add_u32_e32 v0, 0xc80, v8
	s_ashr_i32 s39, s38, 31
	s_mov_b32 s57, s56
	v_lshl_add_u64 v[4:5], s[38:39], 1, v[16:17]
	v_lshlrev_b64 v[6:7], 12, v[0:1]
	s_mov_b32 s58, s56
	s_mov_b32 s59, s56
	v_mov_b64_e32 v[34:35], s[56:57]
	v_lshl_add_u64 v[6:7], v[4:5], 0, v[6:7]
	v_mov_b64_e32 v[36:37], s[58:59]
	v_add_u32_e32 v0, 0xc88, v8
	global_store_dwordx4 v[6:7], v[34:37], off sc1
	v_lshlrev_b64 v[6:7], 12, v[0:1]
	v_lshl_add_u64 v[6:7], v[4:5], 0, v[6:7]
	v_add_u32_e32 v0, 0xc90, v8
	global_store_dwordx4 v[6:7], v[34:37], off sc1
	v_lshlrev_b64 v[6:7], 12, v[0:1]
	v_lshl_add_u64 v[6:7], v[4:5], 0, v[6:7]
	v_add_u32_e32 v0, 0xc98, v8
	global_store_dwordx4 v[6:7], v[34:37], off sc1
	v_lshlrev_b64 v[6:7], 12, v[0:1]
	v_lshl_add_u64 v[4:5], v[4:5], 0, v[6:7]
	global_store_dwordx4 v[4:5], v[34:37], off sc1

.LBB0_1073:
	s_lshr_b32 s13, s11, 31
	s_add_i32 s13, s11, s13
	s_lshl_b32 s13, s13, 5
	s_and_b32 s38, s13, 0xffffffc0
	s_andn2_b64 vcc, exec, s[30:31]
	s_sub_i32 s13, 0, s38
	s_cbranch_vccnz .LBB0_1075
	s_add_i32 s42, s12, s13
	v_or_b32_e32 v8, s38, v20
	s_ashr_i32 s43, s42, 31
	v_ashrrev_i32_e32 v9, 31, v8
	v_or_b32_e32 v34, 8, v8
	v_or_b32_e32 v38, 16, v8
	v_lshl_add_u64 v[18:19], s[42:43], 2, v[2:3]
	v_lshlrev_b64 v[4:5], 8, v[8:9]
	v_ashrrev_i32_e32 v35, 31, v34
	v_ashrrev_i32_e32 v39, 31, v38
	v_lshl_add_u64 v[4:5], v[18:19], 0, v[4:5]
	v_lshlrev_b64 v[34:35], 8, v[34:35]
	v_lshlrev_b64 v[38:39], 8, v[38:39]
	v_or_b32_e32 v42, 24, v8
	global_load_dwordx4 v[4:7], v[4:5], off nt
	v_lshl_add_u64 v[34:35], v[18:19], 0, v[34:35]
	v_lshl_add_u64 v[38:39], v[18:19], 0, v[38:39]
	v_ashrrev_i32_e32 v43, 31, v42
	v_or_b32_e32 v46, 32, v8
	global_load_dwordx4 v[34:37], v[34:35], off nt
	v_lshlrev_b64 v[42:43], 8, v[42:43]
	global_load_dwordx4 v[38:41], v[38:39], off nt
	v_ashrrev_i32_e32 v47, 31, v46
	v_lshl_add_u64 v[42:43], v[18:19], 0, v[42:43]
	v_lshlrev_b64 v[46:47], 8, v[46:47]
	v_or_b32_e32 v50, 40, v8
	global_load_dwordx4 v[42:45], v[42:43], off nt
	v_lshl_add_u64 v[46:47], v[18:19], 0, v[46:47]
	v_ashrrev_i32_e32 v51, 31, v50
	global_load_dwordx4 v[46:49], v[46:47], off nt
	v_lshlrev_b64 v[50:51], 8, v[50:51]
	v_or_b32_e32 v54, 48, v8
	v_lshl_add_u64 v[50:51], v[18:19], 0, v[50:51]
	v_ashrrev_i32_e32 v55, 31, v54
	global_load_dwordx4 v[50:53], v[50:51], off nt
	v_lshlrev_b64 v[54:55], 8, v[54:55]
	v_or_b32_e32 v8, 56, v8
	v_lshl_add_u64 v[54:55], v[18:19], 0, v[54:55]
	v_ashrrev_i32_e32 v9, 31, v8
	global_load_dwordx4 v[54:57], v[54:55], off nt
	v_lshlrev_b64 v[8:9], 8, v[8:9]
	v_lshl_add_u64 v[8:9], v[18:19], 0, v[8:9]
	global_load_dwordx4 v[58:61], v[8:9], off nt
	v_add_u32_e32 v0, v21, v23
	v_add_u32_e32 v11, s42, v13
	s_ashr_i32 s39, s38, 31
	s_waitcnt vmcnt(7)
	ds_write2_b32 v22, v4, v5 offset1:1
	ds_write2_b32 v22, v6, v7 offset0:2 offset1:3
	v_add_u32_e32 v4, 0x420, v0
	s_waitcnt vmcnt(6)
	ds_write2_b32 v0, v34, v35 offset1:1
	ds_write2_b32 v0, v36, v37 offset0:2 offset1:3
	s_waitcnt vmcnt(5)
	ds_write2_b32 v4, v38, v39 offset1:1
	v_add_u32_e32 v4, 0x428, v0
	ds_write2_b32 v4, v40, v41 offset1:1
	v_add_u32_e32 v4, 0x840, v0
	v_add_u32_e32 v0, 0x848, v0
	s_waitcnt vmcnt(4)
	ds_write2_b32 v0, v44, v45 offset1:1
	v_add_u32_e32 v0, 0x1080, v22
	ds_write2_b32 v4, v42, v43 offset1:1
	s_waitcnt vmcnt(3)
	ds_write2_b32 v0, v46, v47 offset1:1
	v_add_u32_e32 v0, 0x1088, v22
	ds_write2_b32 v0, v48, v49 offset1:1
	v_add_u32_e32 v0, 0x14a0, v22
	v_lshl_add_u64 v[4:5], s[38:39], 1, v[16:17]
	s_waitcnt vmcnt(2)
	ds_write2_b32 v0, v50, v51 offset1:1
	v_add_u32_e32 v0, 0x14a8, v22
	ds_write2_b32 v0, v52, v53 offset1:1
	v_add_u32_e32 v0, 0x18c0, v22
	s_waitcnt vmcnt(1)
	ds_write2_b32 v0, v54, v55 offset1:1
	v_add_u32_e32 v0, 0x18c8, v22
	ds_write2_b32 v0, v56, v57 offset1:1
	v_add_u32_e32 v0, 0x1ce0, v22
	s_waitcnt vmcnt(0)
	ds_write2_b32 v0, v58, v59 offset1:1
	v_add_u32_e32 v0, 0x1ce8, v22
	ds_write2_b32 v0, v60, v61 offset1:1
	s_waitcnt lgkmcnt(0)
	ds_read2_b32 v[18:19], v24 offset0:33 offset1:41
	ds_read2_b32 v[34:35], v24 offset1:8
	ds_read2_b32 v[36:37], v24 offset0:66 offset1:74
	ds_read2_b32 v[38:39], v24 offset0:99 offset1:107
	ds_read2_b32 v[40:41], v24 offset0:132 offset1:140
	ds_read2_b32 v[42:43], v24 offset0:165 offset1:173
	ds_read2_b32 v[44:45], v24 offset0:198 offset1:206
	ds_read2_b32 v[46:47], v24 offset0:231 offset1:239
	v_add_u32_e32 v0, 0xc80, v11
	v_lshlrev_b64 v[48:49], 12, v[0:1]
	s_waitcnt lgkmcnt(6)
	v_cvt_pk_bf16_f32 v6, v34, v18
	s_waitcnt lgkmcnt(4)
	v_cvt_pk_bf16_f32 v7, v36, v38
	s_waitcnt lgkmcnt(2)
	v_cvt_pk_bf16_f32 v8, v40, v42
	s_waitcnt lgkmcnt(0)
	v_cvt_pk_bf16_f32 v9, v44, v46
	v_lshl_add_u64 v[48:49], v[4:5], 0, v[48:49]
	v_add_u32_e32 v0, 0xc88, v11
	global_store_dwordx4 v[48:49], v[6:9], off sc1
	s_nop 1
	v_cvt_pk_bf16_f32 v6, v35, v19
	v_lshlrev_b64 v[18:19], 12, v[0:1]
	v_cvt_pk_bf16_f32 v7, v37, v39
	v_cvt_pk_bf16_f32 v8, v41, v43
	v_cvt_pk_bf16_f32 v9, v45, v47
	v_lshl_add_u64 v[18:19], v[4:5], 0, v[18:19]
	global_store_dwordx4 v[18:19], v[6:9], off sc1
	ds_read2_b32 v[18:19], v24 offset0:49 offset1:57
	ds_read2_b32 v[34:35], v24 offset0:16 offset1:24
	ds_read2_b32 v[36:37], v24 offset0:82 offset1:90
	ds_read2_b32 v[38:39], v24 offset0:115 offset1:123
	ds_read2_b32 v[40:41], v24 offset0:148 offset1:156
	ds_read2_b32 v[42:43], v24 offset0:181 offset1:189
	ds_read2_b32 v[44:45], v24 offset0:214 offset1:222
	ds_read2_b32 v[46:47], v24 offset0:247 offset1:255
	v_add_u32_e32 v0, 0xc90, v11
	v_lshlrev_b64 v[48:49], 12, v[0:1]
	s_waitcnt lgkmcnt(6)
	v_cvt_pk_bf16_f32 v6, v34, v18
	s_waitcnt lgkmcnt(4)
	v_cvt_pk_bf16_f32 v7, v36, v38
	s_waitcnt lgkmcnt(2)
	v_cvt_pk_bf16_f32 v8, v40, v42
	s_waitcnt lgkmcnt(0)
	v_cvt_pk_bf16_f32 v9, v44, v46
	v_lshl_add_u64 v[48:49], v[4:5], 0, v[48:49]
	v_add_u32_e32 v0, 0xc98, v11
	global_store_dwordx4 v[48:49], v[6:9], off sc1
	s_nop 1
	v_cvt_pk_bf16_f32 v6, v35, v19
	v_lshlrev_b64 v[18:19], 12, v[0:1]
	v_cvt_pk_bf16_f32 v7, v37, v39
	v_cvt_pk_bf16_f32 v8, v41, v43
	v_cvt_pk_bf16_f32 v9, v45, v47
	v_lshl_add_u64 v[4:5], v[4:5], 0, v[18:19]
	global_store_dwordx4 v[4:5], v[6:9], off sc1
	s_waitcnt lgkmcnt(0)
	s_cbranch_execnz .LBB0_1072
	s_branch .LBB0_1071

.LBB0_1078:
	s_add_i32 s12, s12, s11
	v_add_u32_e32 v6, s12, v13
	v_add_u32_e32 v0, 0xc80, v6
	s_ashr_i32 s35, s34, 31
	s_mov_b32 s57, s56
	v_lshl_add_u64 v[2:3], s[34:35], 1, v[14:15]
	v_lshlrev_b64 v[4:5], 12, v[0:1]
	s_mov_b32 s58, s56
	s_mov_b32 s59, s56
	v_mov_b64_e32 v[34:35], s[56:57]
	v_lshl_add_u64 v[4:5], v[2:3], 0, v[4:5]
	v_mov_b64_e32 v[36:37], s[58:59]
	v_add_u32_e32 v0, 0xc88, v6
	global_store_dwordx4 v[4:5], v[34:37], off sc1
	v_lshlrev_b64 v[4:5], 12, v[0:1]
	v_lshl_add_u64 v[4:5], v[2:3], 0, v[4:5]
	v_add_u32_e32 v0, 0xc90, v6
	global_store_dwordx4 v[4:5], v[34:37], off sc1
	v_lshlrev_b64 v[4:5], 12, v[0:1]
	v_lshl_add_u64 v[4:5], v[2:3], 0, v[4:5]
	v_add_u32_e32 v0, 0xc98, v6
	global_store_dwordx4 v[4:5], v[34:37], off sc1
	v_lshlrev_b64 v[4:5], 12, v[0:1]
	v_lshl_add_u64 v[2:3], v[2:3], 0, v[4:5]
	global_store_dwordx4 v[2:3], v[34:37], off sc1

.LBB0_1080:
	s_lshr_b32 s12, s10, 31
	s_add_i32 s12, s10, s12
	s_lshl_b32 s12, s12, 5
	s_and_b32 s34, s12, 0xffffffc0
	s_andn2_b64 vcc, exec, s[30:31]
	s_sub_i32 s12, 0, s34
	s_cbranch_vccnz .LBB0_1082
	s_add_i32 s36, s11, s12
	v_or_b32_e32 v58, s34, v20
	s_ashr_i32 s37, s36, 31
	v_ashrrev_i32_e32 v59, 31, v58
	v_lshl_add_u64 v[2:3], s[36:37], 2, v[18:19]
	v_lshlrev_b64 v[4:5], 8, v[58:59]
	v_lshl_add_u64 v[4:5], v[2:3], 0, v[4:5]
	global_load_dwordx4 v[34:37], v[4:5], off nt
	v_or_b32_e32 v4, 8, v58
	v_ashrrev_i32_e32 v5, 31, v4
	v_lshlrev_b64 v[4:5], 8, v[4:5]
	v_lshl_add_u64 v[4:5], v[2:3], 0, v[4:5]
	global_load_dwordx4 v[38:41], v[4:5], off nt
	v_or_b32_e32 v4, 16, v58
	v_ashrrev_i32_e32 v5, 31, v4
	v_lshlrev_b64 v[4:5], 8, v[4:5]
	v_lshl_add_u64 v[4:5], v[2:3], 0, v[4:5]
	global_load_dwordx4 v[42:45], v[4:5], off nt
	v_or_b32_e32 v4, 24, v58
	v_ashrrev_i32_e32 v5, 31, v4
	v_lshlrev_b64 v[4:5], 8, v[4:5]
	v_lshl_add_u64 v[4:5], v[2:3], 0, v[4:5]
	global_load_dwordx4 v[46:49], v[4:5], off nt
	v_or_b32_e32 v4, 32, v58
	v_ashrrev_i32_e32 v5, 31, v4
	v_lshlrev_b64 v[4:5], 8, v[4:5]
	v_lshl_add_u64 v[4:5], v[2:3], 0, v[4:5]
	global_load_dwordx4 v[50:53], v[4:5], off nt
	v_or_b32_e32 v4, 40, v58
	v_ashrrev_i32_e32 v5, 31, v4
	v_lshlrev_b64 v[4:5], 8, v[4:5]
	v_lshl_add_u64 v[4:5], v[2:3], 0, v[4:5]
	global_load_dwordx4 v[54:57], v[4:5], off nt
	v_or_b32_e32 v4, 48, v58
	v_ashrrev_i32_e32 v5, 31, v4
	v_lshlrev_b64 v[4:5], 8, v[4:5]
	v_lshl_add_u64 v[4:5], v[2:3], 0, v[4:5]
	global_load_dwordx4 v[6:9], v[4:5], off nt
	v_or_b32_e32 v4, 56, v58
	v_lshl_add_u64 v[58:59], v[58:59], 2, s[26:27]
	global_load_dword v0, v[58:59], off
	v_ashrrev_i32_e32 v5, 31, v4
	v_lshlrev_b64 v[4:5], 8, v[4:5]
	v_lshl_add_u64 v[2:3], v[2:3], 0, v[4:5]
	global_load_dwordx4 v[2:5], v[2:3], off nt
	v_add_u32_e32 v11, v21, v23
	s_ashr_i32 s35, s34, 31
	s_waitcnt vmcnt(1)
	v_pk_mul_f32 v[34:35], v[34:35], v[0:1] op_sel_hi:[1,0]
	v_pk_mul_f32 v[36:37], v[36:37], v[0:1] op_sel_hi:[1,0]
	ds_write2_b32 v22, v34, v35 offset1:1
	ds_write2_b32 v22, v36, v37 offset0:2 offset1:3
	v_or_b32_e32 v34, s34, v26
	v_ashrrev_i32_e32 v35, 31, v34
	v_lshl_add_u64 v[34:35], v[34:35], 2, s[26:27]
	global_load_dword v0, v[34:35], off
	s_waitcnt vmcnt(0)
	v_pk_mul_f32 v[34:35], v[40:41], v[0:1] op_sel_hi:[1,0]
	v_pk_mul_f32 v[36:37], v[38:39], v[0:1] op_sel_hi:[1,0]
	ds_write2_b32 v11, v36, v37 offset1:1
	ds_write2_b32 v11, v34, v35 offset0:2 offset1:3
	v_or_b32_e32 v34, s34, v27
	v_ashrrev_i32_e32 v35, 31, v34
	v_lshl_add_u64 v[34:35], v[34:35], 2, s[26:27]
	global_load_dword v0, v[34:35], off
	s_waitcnt vmcnt(0)
	v_pk_mul_f32 v[34:35], v[44:45], v[0:1] op_sel_hi:[1,0]
	v_pk_mul_f32 v[36:37], v[42:43], v[0:1] op_sel_hi:[1,0]
	v_add_u32_e32 v0, 0x420, v11
	ds_write2_b32 v0, v36, v37 offset1:1
	v_add_u32_e32 v0, 0x428, v11
	ds_write2_b32 v0, v34, v35 offset1:1
	v_or_b32_e32 v34, s34, v25
	v_ashrrev_i32_e32 v35, 31, v34
	v_lshl_add_u64 v[34:35], v[34:35], 2, s[26:27]
	global_load_dword v0, v[34:35], off
	s_waitcnt vmcnt(0)
	v_pk_mul_f32 v[34:35], v[48:49], v[0:1] op_sel_hi:[1,0]
	v_pk_mul_f32 v[36:37], v[46:47], v[0:1] op_sel_hi:[1,0]
	v_add_u32_e32 v0, 0x840, v11
	ds_write2_b32 v0, v36, v37 offset1:1
	v_add_u32_e32 v0, 0x848, v11
	ds_write2_b32 v0, v34, v35 offset1:1
	v_or_b32_e32 v34, s34, v28
	v_ashrrev_i32_e32 v35, 31, v34
	v_lshl_add_u64 v[34:35], v[34:35], 2, s[26:27]
	global_load_dword v0, v[34:35], off
	v_add_u32_e32 v11, v21, v29
	s_waitcnt vmcnt(0)
	v_pk_mul_f32 v[34:35], v[52:53], v[0:1] op_sel_hi:[1,0]
	v_pk_mul_f32 v[36:37], v[50:51], v[0:1] op_sel_hi:[1,0]
	ds_write2_b32 v11, v36, v37 offset1:1
	ds_write2_b32 v11, v34, v35 offset0:2 offset1:3
	v_or_b32_e32 v34, s34, v30
	v_ashrrev_i32_e32 v35, 31, v34
	v_lshl_add_u64 v[34:35], v[34:35], 2, s[26:27]
	global_load_dword v0, v[34:35], off
	s_waitcnt vmcnt(0)
	v_pk_mul_f32 v[34:35], v[56:57], v[0:1] op_sel_hi:[1,0]
	v_pk_mul_f32 v[36:37], v[54:55], v[0:1] op_sel_hi:[1,0]
	v_add_u32_e32 v0, 0x420, v11
	ds_write2_b32 v0, v36, v37 offset1:1
	v_add_u32_e32 v0, 0x428, v11
	ds_write2_b32 v0, v34, v35 offset1:1
	v_or_b32_e32 v34, s34, v31
	v_ashrrev_i32_e32 v35, 31, v34
	v_lshl_add_u64 v[34:35], v[34:35], 2, s[26:27]
	global_load_dword v0, v[34:35], off
	s_waitcnt vmcnt(0)
	v_pk_mul_f32 v[8:9], v[8:9], v[0:1] op_sel_hi:[1,0]
	v_pk_mul_f32 v[6:7], v[6:7], v[0:1] op_sel_hi:[1,0]
	v_add_u32_e32 v0, 0x840, v11
	ds_write2_b32 v0, v6, v7 offset1:1
	v_or_b32_e32 v6, s34, v32
	v_ashrrev_i32_e32 v7, 31, v6
	v_add_u32_e32 v0, 0x848, v11
	v_lshl_add_u64 v[6:7], v[6:7], 2, s[26:27]
	ds_write2_b32 v0, v8, v9 offset1:1
	global_load_dword v0, v[6:7], off
	v_lshl_add_u64 v[6:7], s[34:35], 1, v[14:15]
	s_waitcnt vmcnt(0)
	v_pk_mul_f32 v[4:5], v[4:5], v[0:1] op_sel_hi:[1,0]
	v_pk_mul_f32 v[2:3], v[2:3], v[0:1] op_sel_hi:[1,0]
	v_add_u32_e32 v0, 0xc60, v11
	ds_write2_b32 v0, v2, v3 offset1:1
	v_add_u32_e32 v0, 0xc68, v11
	ds_write2_b32 v0, v4, v5 offset1:1
	s_waitcnt lgkmcnt(0)
	ds_read2_b32 v[8:9], v24 offset0:33 offset1:41
	ds_read2_b32 v[34:35], v24 offset1:8
	ds_read2_b32 v[36:37], v24 offset0:66 offset1:74
	ds_read2_b32 v[38:39], v24 offset0:99 offset1:107
	ds_read2_b32 v[40:41], v24 offset0:132 offset1:140
	ds_read2_b32 v[42:43], v24 offset0:165 offset1:173
	ds_read2_b32 v[44:45], v24 offset0:198 offset1:206
	ds_read2_b32 v[46:47], v24 offset0:231 offset1:239
	v_add_u32_e32 v11, s36, v13
	v_add_u32_e32 v0, 0xc80, v11
	v_lshlrev_b64 v[48:49], 12, v[0:1]
	s_waitcnt lgkmcnt(6)
	v_cvt_pk_bf16_f32 v2, v34, v8
	s_waitcnt lgkmcnt(4)
	v_cvt_pk_bf16_f32 v3, v36, v38
	s_waitcnt lgkmcnt(2)
	v_cvt_pk_bf16_f32 v4, v40, v42
	s_waitcnt lgkmcnt(0)
	v_cvt_pk_bf16_f32 v5, v44, v46
	v_lshl_add_u64 v[48:49], v[6:7], 0, v[48:49]
	v_add_u32_e32 v0, 0xc88, v11
	global_store_dwordx4 v[48:49], v[2:5], off sc1
	s_nop 1
	v_cvt_pk_bf16_f32 v2, v35, v9
	v_lshlrev_b64 v[8:9], 12, v[0:1]
	v_cvt_pk_bf16_f32 v3, v37, v39
	v_cvt_pk_bf16_f32 v4, v41, v43
	v_cvt_pk_bf16_f32 v5, v45, v47
	v_lshl_add_u64 v[8:9], v[6:7], 0, v[8:9]
	global_store_dwordx4 v[8:9], v[2:5], off sc1
	ds_read2_b32 v[8:9], v24 offset0:49 offset1:57
	ds_read2_b32 v[34:35], v24 offset0:16 offset1:24
	ds_read2_b32 v[36:37], v24 offset0:82 offset1:90
	ds_read2_b32 v[38:39], v24 offset0:115 offset1:123
	ds_read2_b32 v[40:41], v24 offset0:148 offset1:156
	ds_read2_b32 v[42:43], v24 offset0:181 offset1:189
	ds_read2_b32 v[44:45], v24 offset0:214 offset1:222
	ds_read2_b32 v[46:47], v24 offset0:247 offset1:255
	v_add_u32_e32 v0, 0xc90, v11
	v_lshlrev_b64 v[48:49], 12, v[0:1]
	s_waitcnt lgkmcnt(6)
	v_cvt_pk_bf16_f32 v2, v34, v8
	s_waitcnt lgkmcnt(4)
	v_cvt_pk_bf16_f32 v3, v36, v38
	s_waitcnt lgkmcnt(2)
	v_cvt_pk_bf16_f32 v4, v40, v42
	s_waitcnt lgkmcnt(0)
	v_cvt_pk_bf16_f32 v5, v44, v46
	v_lshl_add_u64 v[48:49], v[6:7], 0, v[48:49]
	v_add_u32_e32 v0, 0xc98, v11
	global_store_dwordx4 v[48:49], v[2:5], off sc1
	s_nop 1
	v_cvt_pk_bf16_f32 v2, v35, v9
	v_lshlrev_b64 v[8:9], 12, v[0:1]
	v_cvt_pk_bf16_f32 v3, v37, v39
	v_cvt_pk_bf16_f32 v4, v41, v43
	v_cvt_pk_bf16_f32 v5, v45, v47
	v_lshl_add_u64 v[6:7], v[6:7], 0, v[8:9]
	global_store_dwordx4 v[6:7], v[2:5], off sc1
	s_waitcnt lgkmcnt(0)
	s_cbranch_execnz .LBB0_1079
	s_branch .LBB0_1078

.LBB0_1085:
	s_add_i32 s11, s11, s10
	v_add_u32_e32 v8, s11, v20
	v_add_u32_e32 v0, 0xd00, v8
	s_ashr_i32 s19, s18, 31
	s_mov_b32 s57, s56
	v_lshl_add_u64 v[4:5], s[18:19], 1, v[16:17]
	v_lshlrev_b64 v[6:7], 12, v[0:1]
	s_mov_b32 s58, s56
	s_mov_b32 s59, s56
	v_mov_b64_e32 v[34:35], s[56:57]
	v_lshl_add_u64 v[6:7], v[4:5], 0, v[6:7]
	v_mov_b64_e32 v[36:37], s[58:59]
	v_add_u32_e32 v0, 0xd08, v8
	global_store_dwordx4 v[6:7], v[34:37], off sc1
	v_lshlrev_b64 v[6:7], 12, v[0:1]
	v_lshl_add_u64 v[6:7], v[4:5], 0, v[6:7]
	v_add_u32_e32 v0, 0xd10, v8
	global_store_dwordx4 v[6:7], v[34:37], off sc1
	v_lshlrev_b64 v[6:7], 12, v[0:1]
	v_lshl_add_u64 v[6:7], v[4:5], 0, v[6:7]
	v_add_u32_e32 v0, 0xd18, v8
	global_store_dwordx4 v[6:7], v[34:37], off sc1
	v_lshlrev_b64 v[6:7], 12, v[0:1]
	v_lshl_add_u64 v[4:5], v[4:5], 0, v[6:7]
	global_store_dwordx4 v[4:5], v[34:37], off sc1

.LBB0_1087:
	s_ashr_i32 s11, s9, 31
	s_lshr_b32 s11, s11, 30
	s_add_i32 s11, s9, s11
	s_ashr_i32 s11, s11, 2
	s_lshl_b32 s18, s11, 6
	s_lshl_b32 s11, s11, 7
	s_andn2_b64 vcc, exec, s[14:15]
	s_sub_i32 s11, 0, s11
	s_cbranch_vccnz .LBB0_1089
	s_add_i32 s26, s10, s11
	v_or_b32_e32 v8, s18, v20
	s_ashr_i32 s27, s26, 31
	v_ashrrev_i32_e32 v9, 31, v8
	v_or_b32_e32 v34, 8, v8
	v_or_b32_e32 v38, 16, v8
	v_lshl_add_u64 v[18:19], s[26:27], 2, v[2:3]
	v_lshlrev_b64 v[4:5], 9, v[8:9]
	v_ashrrev_i32_e32 v35, 31, v34
	v_ashrrev_i32_e32 v39, 31, v38
	v_lshl_add_u64 v[4:5], v[18:19], 0, v[4:5]
	v_lshlrev_b64 v[34:35], 9, v[34:35]
	v_lshlrev_b64 v[38:39], 9, v[38:39]
	v_or_b32_e32 v42, 24, v8
	global_load_dwordx4 v[4:7], v[4:5], off nt
	v_lshl_add_u64 v[34:35], v[18:19], 0, v[34:35]
	v_lshl_add_u64 v[38:39], v[18:19], 0, v[38:39]
	v_ashrrev_i32_e32 v43, 31, v42
	v_or_b32_e32 v46, 32, v8
	global_load_dwordx4 v[34:37], v[34:35], off nt
	v_lshlrev_b64 v[42:43], 9, v[42:43]
	global_load_dwordx4 v[38:41], v[38:39], off nt
	v_ashrrev_i32_e32 v47, 31, v46
	v_lshl_add_u64 v[42:43], v[18:19], 0, v[42:43]
	v_lshlrev_b64 v[46:47], 9, v[46:47]
	v_or_b32_e32 v50, 40, v8
	global_load_dwordx4 v[42:45], v[42:43], off nt
	v_lshl_add_u64 v[46:47], v[18:19], 0, v[46:47]
	v_ashrrev_i32_e32 v51, 31, v50
	global_load_dwordx4 v[46:49], v[46:47], off nt
	v_lshlrev_b64 v[50:51], 9, v[50:51]
	v_or_b32_e32 v54, 48, v8
	v_lshl_add_u64 v[50:51], v[18:19], 0, v[50:51]
	v_ashrrev_i32_e32 v55, 31, v54
	global_load_dwordx4 v[50:53], v[50:51], off nt
	v_lshlrev_b64 v[54:55], 9, v[54:55]
	v_or_b32_e32 v8, 56, v8
	v_lshl_add_u64 v[54:55], v[18:19], 0, v[54:55]
	v_ashrrev_i32_e32 v9, 31, v8
	global_load_dwordx4 v[54:57], v[54:55], off nt
	v_lshlrev_b64 v[8:9], 9, v[8:9]
	v_lshl_add_u64 v[8:9], v[18:19], 0, v[8:9]
	global_load_dwordx4 v[58:61], v[8:9], off nt
	v_add_u32_e32 v0, v21, v23
	v_add_u32_e32 v11, s26, v20
	s_ashr_i32 s19, s18, 31
	s_waitcnt vmcnt(7)
	ds_write2_b32 v22, v4, v5 offset1:1
	ds_write2_b32 v22, v6, v7 offset0:2 offset1:3
	v_add_u32_e32 v4, 0x420, v0
	s_waitcnt vmcnt(6)
	ds_write2_b32 v0, v34, v35 offset1:1
	ds_write2_b32 v0, v36, v37 offset0:2 offset1:3
	s_waitcnt vmcnt(5)
	ds_write2_b32 v4, v38, v39 offset1:1
	v_add_u32_e32 v4, 0x428, v0
	ds_write2_b32 v4, v40, v41 offset1:1
	v_add_u32_e32 v4, 0x840, v0
	v_add_u32_e32 v0, 0x848, v0
	s_waitcnt vmcnt(4)
	ds_write2_b32 v0, v44, v45 offset1:1
	v_add_u32_e32 v0, 0x1080, v22
	ds_write2_b32 v4, v42, v43 offset1:1
	s_waitcnt vmcnt(3)
	ds_write2_b32 v0, v46, v47 offset1:1
	v_add_u32_e32 v0, 0x1088, v22
	ds_write2_b32 v0, v48, v49 offset1:1
	v_add_u32_e32 v0, 0x14a0, v22
	v_lshl_add_u64 v[4:5], s[18:19], 1, v[16:17]
	s_waitcnt vmcnt(2)
	ds_write2_b32 v0, v50, v51 offset1:1
	v_add_u32_e32 v0, 0x14a8, v22
	ds_write2_b32 v0, v52, v53 offset1:1
	v_add_u32_e32 v0, 0x18c0, v22
	s_waitcnt vmcnt(1)
	ds_write2_b32 v0, v54, v55 offset1:1
	v_add_u32_e32 v0, 0x18c8, v22
	ds_write2_b32 v0, v56, v57 offset1:1
	v_add_u32_e32 v0, 0x1ce0, v22
	s_waitcnt vmcnt(0)
	ds_write2_b32 v0, v58, v59 offset1:1
	v_add_u32_e32 v0, 0x1ce8, v22
	ds_write2_b32 v0, v60, v61 offset1:1
	s_waitcnt lgkmcnt(0)
	ds_read2_b32 v[18:19], v24 offset0:33 offset1:41
	ds_read2_b32 v[34:35], v24 offset1:8
	ds_read2_b32 v[36:37], v24 offset0:66 offset1:74
	ds_read2_b32 v[38:39], v24 offset0:99 offset1:107
	ds_read2_b32 v[40:41], v24 offset0:132 offset1:140
	ds_read2_b32 v[42:43], v24 offset0:165 offset1:173
	ds_read2_b32 v[44:45], v24 offset0:198 offset1:206
	ds_read2_b32 v[46:47], v24 offset0:231 offset1:239
	v_add_u32_e32 v0, 0xd00, v11
	v_lshlrev_b64 v[48:49], 12, v[0:1]
	s_waitcnt lgkmcnt(6)
	v_cvt_pk_bf16_f32 v6, v34, v18
	s_waitcnt lgkmcnt(4)
	v_cvt_pk_bf16_f32 v7, v36, v38
	s_waitcnt lgkmcnt(2)
	v_cvt_pk_bf16_f32 v8, v40, v42
	s_waitcnt lgkmcnt(0)
	v_cvt_pk_bf16_f32 v9, v44, v46
	v_lshl_add_u64 v[48:49], v[4:5], 0, v[48:49]
	v_add_u32_e32 v0, 0xd08, v11
	global_store_dwordx4 v[48:49], v[6:9], off sc1
	s_nop 1
	v_cvt_pk_bf16_f32 v6, v35, v19
	v_lshlrev_b64 v[18:19], 12, v[0:1]
	v_cvt_pk_bf16_f32 v7, v37, v39
	v_cvt_pk_bf16_f32 v8, v41, v43
	v_cvt_pk_bf16_f32 v9, v45, v47
	v_lshl_add_u64 v[18:19], v[4:5], 0, v[18:19]
	global_store_dwordx4 v[18:19], v[6:9], off sc1
	ds_read2_b32 v[18:19], v24 offset0:49 offset1:57
	ds_read2_b32 v[34:35], v24 offset0:16 offset1:24
	ds_read2_b32 v[36:37], v24 offset0:82 offset1:90
	ds_read2_b32 v[38:39], v24 offset0:115 offset1:123
	ds_read2_b32 v[40:41], v24 offset0:148 offset1:156
	ds_read2_b32 v[42:43], v24 offset0:181 offset1:189
	ds_read2_b32 v[44:45], v24 offset0:214 offset1:222
	ds_read2_b32 v[46:47], v24 offset0:247 offset1:255
	v_add_u32_e32 v0, 0xd10, v11
	v_lshlrev_b64 v[48:49], 12, v[0:1]
	s_waitcnt lgkmcnt(6)
	v_cvt_pk_bf16_f32 v6, v34, v18
	s_waitcnt lgkmcnt(4)
	v_cvt_pk_bf16_f32 v7, v36, v38
	s_waitcnt lgkmcnt(2)
	v_cvt_pk_bf16_f32 v8, v40, v42
	s_waitcnt lgkmcnt(0)
	v_cvt_pk_bf16_f32 v9, v44, v46
	v_lshl_add_u64 v[48:49], v[4:5], 0, v[48:49]
	v_add_u32_e32 v0, 0xd18, v11
	global_store_dwordx4 v[48:49], v[6:9], off sc1
	s_nop 1
	v_cvt_pk_bf16_f32 v6, v35, v19
	v_lshlrev_b64 v[18:19], 12, v[0:1]
	v_cvt_pk_bf16_f32 v7, v37, v39
	v_cvt_pk_bf16_f32 v8, v41, v43
	v_cvt_pk_bf16_f32 v9, v45, v47
	v_lshl_add_u64 v[4:5], v[4:5], 0, v[18:19]
	global_store_dwordx4 v[4:5], v[6:9], off sc1
	s_waitcnt lgkmcnt(0)
	s_cbranch_execnz .LBB0_1086
	s_branch .LBB0_1085

.LBB0_1092:
	s_add_i32 s11, s11, s10
	v_add_u32_e32 v6, s11, v20
	v_add_u32_e32 v0, 0xd00, v6
	s_ashr_i32 s25, s24, 31
	s_mov_b32 s57, s56
	v_lshl_add_u64 v[2:3], s[24:25], 1, v[14:15]
	v_lshlrev_b64 v[4:5], 12, v[0:1]
	s_mov_b32 s58, s56
	s_mov_b32 s59, s56
	v_mov_b64_e32 v[34:35], s[56:57]
	v_lshl_add_u64 v[4:5], v[2:3], 0, v[4:5]
	v_mov_b64_e32 v[36:37], s[58:59]
	v_add_u32_e32 v0, 0xd08, v6
	global_store_dwordx4 v[4:5], v[34:37], off sc1
	v_lshlrev_b64 v[4:5], 12, v[0:1]
	v_lshl_add_u64 v[4:5], v[2:3], 0, v[4:5]
	v_add_u32_e32 v0, 0xd10, v6
	global_store_dwordx4 v[4:5], v[34:37], off sc1
	v_lshlrev_b64 v[4:5], 12, v[0:1]
	v_lshl_add_u64 v[4:5], v[2:3], 0, v[4:5]
	v_add_u32_e32 v0, 0xd18, v6
	global_store_dwordx4 v[4:5], v[34:37], off sc1
	v_lshlrev_b64 v[4:5], 12, v[0:1]
	v_lshl_add_u64 v[2:3], v[2:3], 0, v[4:5]
	global_store_dwordx4 v[2:3], v[34:37], off sc1

.LBB0_1094:
	s_ashr_i32 s11, s9, 31
	s_lshr_b32 s11, s11, 30
	s_add_i32 s11, s9, s11
	s_ashr_i32 s11, s11, 2
	s_lshl_b32 s24, s11, 6
	s_lshl_b32 s11, s11, 7
	s_andn2_b64 vcc, exec, s[18:19]
	s_sub_i32 s11, 0, s11
	s_cbranch_vccnz .LBB0_1096
	s_add_i32 s26, s10, s11
	v_or_b32_e32 v18, s24, v20
	s_ashr_i32 s27, s26, 31
	v_ashrrev_i32_e32 v19, 31, v18
	v_lshl_add_u64 v[2:3], s[26:27], 2, v[16:17]
	v_lshlrev_b64 v[4:5], 9, v[18:19]
	v_lshl_add_u64 v[4:5], v[2:3], 0, v[4:5]
	global_load_dwordx4 v[34:37], v[4:5], off nt
	v_or_b32_e32 v4, 8, v18
	v_ashrrev_i32_e32 v5, 31, v4
	v_lshlrev_b64 v[4:5], 9, v[4:5]
	v_lshl_add_u64 v[4:5], v[2:3], 0, v[4:5]
	global_load_dwordx4 v[38:41], v[4:5], off nt
	v_or_b32_e32 v4, 16, v18
	v_ashrrev_i32_e32 v5, 31, v4
	v_lshlrev_b64 v[4:5], 9, v[4:5]
	v_lshl_add_u64 v[4:5], v[2:3], 0, v[4:5]
	global_load_dwordx4 v[42:45], v[4:5], off nt
	v_or_b32_e32 v4, 24, v18
	v_ashrrev_i32_e32 v5, 31, v4
	v_lshlrev_b64 v[4:5], 9, v[4:5]
	v_lshl_add_u64 v[4:5], v[2:3], 0, v[4:5]
	global_load_dwordx4 v[46:49], v[4:5], off nt
	v_or_b32_e32 v4, 32, v18
	v_ashrrev_i32_e32 v5, 31, v4
	v_lshlrev_b64 v[4:5], 9, v[4:5]
	v_lshl_add_u64 v[4:5], v[2:3], 0, v[4:5]
	global_load_dwordx4 v[50:53], v[4:5], off nt
	v_or_b32_e32 v4, 40, v18
	v_ashrrev_i32_e32 v5, 31, v4
	v_lshlrev_b64 v[4:5], 9, v[4:5]
	v_lshl_add_u64 v[4:5], v[2:3], 0, v[4:5]
	global_load_dwordx4 v[54:57], v[4:5], off nt
	v_or_b32_e32 v4, 48, v18
	v_ashrrev_i32_e32 v5, 31, v4
	v_lshlrev_b64 v[4:5], 9, v[4:5]
	v_lshl_add_u64 v[4:5], v[2:3], 0, v[4:5]
	global_load_dwordx4 v[6:9], v[4:5], off nt
	v_or_b32_e32 v4, 56, v18
	v_lshl_add_u64 v[18:19], v[18:19], 2, s[14:15]
	global_load_dword v0, v[18:19], off
	v_ashrrev_i32_e32 v5, 31, v4
	v_lshlrev_b64 v[4:5], 9, v[4:5]
	v_lshl_add_u64 v[2:3], v[2:3], 0, v[4:5]
	global_load_dwordx4 v[2:5], v[2:3], off nt
	v_add_u32_e32 v11, v21, v23
	s_ashr_i32 s25, s24, 31
	s_waitcnt vmcnt(1)
	v_pk_mul_f32 v[18:19], v[36:37], v[0:1] op_sel_hi:[1,0]
	v_pk_mul_f32 v[34:35], v[34:35], v[0:1] op_sel_hi:[1,0]
	ds_write2_b32 v22, v34, v35 offset1:1
	ds_write2_b32 v22, v18, v19 offset0:2 offset1:3
	v_or_b32_e32 v18, s24, v26
	v_ashrrev_i32_e32 v19, 31, v18
	v_lshl_add_u64 v[18:19], v[18:19], 2, s[14:15]
	global_load_dword v0, v[18:19], off
	s_waitcnt vmcnt(0)
	v_pk_mul_f32 v[18:19], v[40:41], v[0:1] op_sel_hi:[1,0]
	v_pk_mul_f32 v[34:35], v[38:39], v[0:1] op_sel_hi:[1,0]
	ds_write2_b32 v11, v34, v35 offset1:1
	ds_write2_b32 v11, v18, v19 offset0:2 offset1:3
	v_or_b32_e32 v18, s24, v27
	v_ashrrev_i32_e32 v19, 31, v18
	v_lshl_add_u64 v[18:19], v[18:19], 2, s[14:15]
	global_load_dword v0, v[18:19], off
	s_waitcnt vmcnt(0)
	v_pk_mul_f32 v[18:19], v[44:45], v[0:1] op_sel_hi:[1,0]
	v_pk_mul_f32 v[34:35], v[42:43], v[0:1] op_sel_hi:[1,0]
	v_add_u32_e32 v0, 0x420, v11
	ds_write2_b32 v0, v34, v35 offset1:1
	v_add_u32_e32 v0, 0x428, v11
	ds_write2_b32 v0, v18, v19 offset1:1
	v_or_b32_e32 v18, s24, v25
	v_ashrrev_i32_e32 v19, 31, v18
	v_lshl_add_u64 v[18:19], v[18:19], 2, s[14:15]
	global_load_dword v0, v[18:19], off
	s_waitcnt vmcnt(0)
	v_pk_mul_f32 v[18:19], v[48:49], v[0:1] op_sel_hi:[1,0]
	v_pk_mul_f32 v[34:35], v[46:47], v[0:1] op_sel_hi:[1,0]
	v_add_u32_e32 v0, 0x840, v11
	ds_write2_b32 v0, v34, v35 offset1:1
	v_add_u32_e32 v0, 0x848, v11
	ds_write2_b32 v0, v18, v19 offset1:1
	v_or_b32_e32 v18, s24, v28
	v_ashrrev_i32_e32 v19, 31, v18
	v_lshl_add_u64 v[18:19], v[18:19], 2, s[14:15]
	global_load_dword v0, v[18:19], off
	v_add_u32_e32 v11, v21, v29
	s_waitcnt vmcnt(0)
	v_pk_mul_f32 v[18:19], v[52:53], v[0:1] op_sel_hi:[1,0]
	v_pk_mul_f32 v[34:35], v[50:51], v[0:1] op_sel_hi:[1,0]
	ds_write2_b32 v11, v34, v35 offset1:1
	ds_write2_b32 v11, v18, v19 offset0:2 offset1:3
	v_or_b32_e32 v18, s24, v30
	v_ashrrev_i32_e32 v19, 31, v18
	v_lshl_add_u64 v[18:19], v[18:19], 2, s[14:15]
	global_load_dword v0, v[18:19], off
	s_waitcnt vmcnt(0)
	v_pk_mul_f32 v[18:19], v[56:57], v[0:1] op_sel_hi:[1,0]
	v_pk_mul_f32 v[34:35], v[54:55], v[0:1] op_sel_hi:[1,0]
	v_add_u32_e32 v0, 0x420, v11
	ds_write2_b32 v0, v34, v35 offset1:1
	v_add_u32_e32 v0, 0x428, v11
	ds_write2_b32 v0, v18, v19 offset1:1
	v_or_b32_e32 v18, s24, v31
	v_ashrrev_i32_e32 v19, 31, v18
	v_lshl_add_u64 v[18:19], v[18:19], 2, s[14:15]
	global_load_dword v0, v[18:19], off
	s_waitcnt vmcnt(0)
	v_pk_mul_f32 v[8:9], v[8:9], v[0:1] op_sel_hi:[1,0]
	v_pk_mul_f32 v[6:7], v[6:7], v[0:1] op_sel_hi:[1,0]
	v_add_u32_e32 v0, 0x840, v11
	ds_write2_b32 v0, v6, v7 offset1:1
	v_or_b32_e32 v6, s24, v32
	v_ashrrev_i32_e32 v7, 31, v6
	v_add_u32_e32 v0, 0x848, v11
	v_lshl_add_u64 v[6:7], v[6:7], 2, s[14:15]
	ds_write2_b32 v0, v8, v9 offset1:1
	global_load_dword v0, v[6:7], off
	v_lshl_add_u64 v[6:7], s[24:25], 1, v[14:15]
	s_waitcnt vmcnt(0)
	v_pk_mul_f32 v[4:5], v[4:5], v[0:1] op_sel_hi:[1,0]
	v_pk_mul_f32 v[2:3], v[2:3], v[0:1] op_sel_hi:[1,0]
	v_add_u32_e32 v0, 0xc60, v11
	ds_write2_b32 v0, v2, v3 offset1:1
	v_add_u32_e32 v0, 0xc68, v11
	ds_write2_b32 v0, v4, v5 offset1:1
	s_waitcnt lgkmcnt(0)
	ds_read2_b32 v[8:9], v24 offset0:33 offset1:41
	ds_read2_b32 v[18:19], v24 offset1:8
	ds_read2_b32 v[34:35], v24 offset0:66 offset1:74
	ds_read2_b32 v[36:37], v24 offset0:99 offset1:107
	ds_read2_b32 v[38:39], v24 offset0:132 offset1:140
	ds_read2_b32 v[40:41], v24 offset0:165 offset1:173
	ds_read2_b32 v[42:43], v24 offset0:198 offset1:206
	ds_read2_b32 v[44:45], v24 offset0:231 offset1:239
	v_add_u32_e32 v11, s26, v20
	v_add_u32_e32 v0, 0xd00, v11
	v_lshlrev_b64 v[46:47], 12, v[0:1]
	s_waitcnt lgkmcnt(6)
	v_cvt_pk_bf16_f32 v2, v18, v8
	s_waitcnt lgkmcnt(4)
	v_cvt_pk_bf16_f32 v3, v34, v36
	s_waitcnt lgkmcnt(2)
	v_cvt_pk_bf16_f32 v4, v38, v40
	s_waitcnt lgkmcnt(0)
	v_cvt_pk_bf16_f32 v5, v42, v44
	v_lshl_add_u64 v[46:47], v[6:7], 0, v[46:47]
	v_add_u32_e32 v0, 0xd08, v11
	global_store_dwordx4 v[46:47], v[2:5], off sc1
	s_nop 1
	v_cvt_pk_bf16_f32 v2, v19, v9
	v_lshlrev_b64 v[8:9], 12, v[0:1]
	v_cvt_pk_bf16_f32 v3, v35, v37
	v_cvt_pk_bf16_f32 v4, v39, v41
	v_cvt_pk_bf16_f32 v5, v43, v45
	v_lshl_add_u64 v[8:9], v[6:7], 0, v[8:9]
	global_store_dwordx4 v[8:9], v[2:5], off sc1
	ds_read2_b32 v[8:9], v24 offset0:49 offset1:57
	ds_read2_b32 v[18:19], v24 offset0:16 offset1:24
	ds_read2_b32 v[34:35], v24 offset0:82 offset1:90
	ds_read2_b32 v[36:37], v24 offset0:115 offset1:123
	ds_read2_b32 v[38:39], v24 offset0:148 offset1:156
	ds_read2_b32 v[40:41], v24 offset0:181 offset1:189
	ds_read2_b32 v[42:43], v24 offset0:214 offset1:222
	ds_read2_b32 v[44:45], v24 offset0:247 offset1:255
	v_add_u32_e32 v0, 0xd10, v11
	v_lshlrev_b64 v[46:47], 12, v[0:1]
	s_waitcnt lgkmcnt(6)
	v_cvt_pk_bf16_f32 v2, v18, v8
	s_waitcnt lgkmcnt(4)
	v_cvt_pk_bf16_f32 v3, v34, v36
	s_waitcnt lgkmcnt(2)
	v_cvt_pk_bf16_f32 v4, v38, v40
	s_waitcnt lgkmcnt(0)
	v_cvt_pk_bf16_f32 v5, v42, v44
	v_lshl_add_u64 v[46:47], v[6:7], 0, v[46:47]
	v_add_u32_e32 v0, 0xd18, v11
	global_store_dwordx4 v[46:47], v[2:5], off sc1
	s_nop 1
	v_cvt_pk_bf16_f32 v2, v19, v9
	v_lshlrev_b64 v[8:9], 12, v[0:1]
	v_cvt_pk_bf16_f32 v3, v35, v37
	v_cvt_pk_bf16_f32 v4, v39, v41
	v_cvt_pk_bf16_f32 v5, v43, v45
	v_lshl_add_u64 v[6:7], v[6:7], 0, v[8:9]
	global_store_dwordx4 v[6:7], v[2:5], off sc1
	s_waitcnt lgkmcnt(0)
	s_cbranch_execnz .LBB0_1093
	s_branch .LBB0_1092

.LBB0_1101:
	s_ashr_i32 s6, s9, 31
	s_lshr_b32 s6, s6, 30
	s_add_i32 s6, s9, s6
	s_ashr_i32 s7, s6, 2
	s_lshl_b32 s6, s7, 6
	s_lshl_b32 s7, s7, 7
	v_subrev_u32_e32 v8, s7, v6
	v_subrev_u32_e32 v0, 24, v8
	s_ashr_i32 s7, s6, 31
	s_mov_b32 s57, s56
	v_lshl_add_u64 v[14:15], s[6:7], 1, v[4:5]
	v_lshlrev_b64 v[16:17], 12, v[0:1]
	s_mov_b32 s58, s56
	s_mov_b32 s59, s56
	v_mov_b64_e32 v[26:27], s[56:57]
	v_lshl_add_u64 v[16:17], v[14:15], 0, v[16:17]
	v_mov_b64_e32 v[28:29], s[58:59]
	v_add_u32_e32 v0, -16, v8
	global_store_dwordx4 v[16:17], v[26:29], off sc1
	v_lshlrev_b64 v[16:17], 12, v[0:1]
	v_lshl_add_u64 v[16:17], v[14:15], 0, v[16:17]
	v_add_u32_e32 v0, -8, v8
	v_mov_b32_e32 v9, v1
	global_store_dwordx4 v[16:17], v[26:29], off sc1
	v_lshlrev_b64 v[16:17], 12, v[0:1]
	v_lshlrev_b64 v[8:9], 12, v[8:9]
	s_add_i32 s6, s9, 0x200
	v_lshl_add_u64 v[16:17], v[14:15], 0, v[16:17]
	v_lshl_add_u64 v[8:9], v[14:15], 0, v[8:9]
	v_add_u32_e32 v6, 0x4000, v6
	s_cmpk_lt_i32 s9, 0xfe80
	s_mov_b32 s9, s6
	global_store_dwordx4 v[16:17], v[26:29], off sc1
	global_store_dwordx4 v[8:9], v[26:29], off sc1
	s_cbranch_scc1 .LBB0_1101

.LBB0_1109:
	s_ashr_i32 s14, s7, 31
	s_lshr_b32 s14, s14, 27
	s_add_i32 s14, s7, s14
	s_ashr_i32 s15, s14, 5
	s_lshl_b32 s14, s15, 6
	v_add_u32_e32 v13, s6, v11
	s_lshl_b32 s15, s15, 10
	v_subrev_u32_e32 v16, s15, v13
	v_subrev_u32_e32 v18, 24, v16
	s_ashr_i32 s15, s14, 31
	v_ashrrev_i32_e32 v19, 31, v18
	s_mov_b32 s57, s56
	v_lshl_add_u64 v[26:27], s[14:15], 1, v[14:15]
	v_lshlrev_b64 v[18:19], 9, v[18:19]
	s_mov_b32 s58, s56
	s_mov_b32 s59, s56
	v_mov_b64_e32 v[28:29], s[56:57]
	v_lshl_add_u64 v[18:19], v[26:27], 0, v[18:19]
	v_mov_b64_e32 v[30:31], s[58:59]
	global_store_dwordx4 v[18:19], v[28:31], off sc1
	v_add_u32_e32 v18, -16, v16
	v_ashrrev_i32_e32 v19, 31, v18
	v_lshlrev_b64 v[18:19], 9, v[18:19]
	v_lshl_add_u64 v[18:19], v[26:27], 0, v[18:19]
	global_store_dwordx4 v[18:19], v[28:31], off sc1
	v_add_u32_e32 v18, -8, v16
	v_ashrrev_i32_e32 v19, 31, v18
	v_ashrrev_i32_e32 v17, 31, v16
	v_lshlrev_b64 v[18:19], 9, v[18:19]
	v_lshlrev_b64 v[16:17], 9, v[16:17]
	s_add_i32 s14, s7, 0x200
	v_lshl_add_u64 v[18:19], v[26:27], 0, v[18:19]
	v_lshl_add_u64 v[16:17], v[26:27], 0, v[16:17]
	v_add_u32_e32 v11, 0x4000, v11
	s_cmpk_lt_i32 s7, 0xfe20
	s_mov_b32 s7, s14
	global_store_dwordx4 v[18:19], v[28:31], off sc1
	global_store_dwordx4 v[16:17], v[28:31], off sc1
	s_cbranch_scc1 .LBB0_1109

.LBB0_1114:
	s_add_i32 s24, s24, s23
	v_add_u32_e32 v16, s24, v0
	s_ashr_i32 s15, s14, 31
	v_ashrrev_i32_e32 v17, 31, v16
	s_mov_b32 s57, s56
	v_lshl_add_u64 v[18:19], s[14:15], 1, v[8:9]
	v_lshlrev_b64 v[26:27], 9, v[16:17]
	s_mov_b32 s58, s56
	s_mov_b32 s59, s56
	v_mov_b64_e32 v[28:29], s[56:57]
	v_lshl_add_u64 v[26:27], v[18:19], 0, v[26:27]
	v_mov_b64_e32 v[30:31], s[58:59]
	global_store_dwordx4 v[26:27], v[28:31], off sc1
	v_add_u32_e32 v26, 8, v16
	v_ashrrev_i32_e32 v27, 31, v26
	v_lshlrev_b64 v[26:27], 9, v[26:27]
	v_lshl_add_u64 v[26:27], v[18:19], 0, v[26:27]
	global_store_dwordx4 v[26:27], v[28:31], off sc1
	v_add_u32_e32 v26, 16, v16
	v_add_u32_e32 v16, 24, v16
	v_ashrrev_i32_e32 v27, 31, v26
	v_ashrrev_i32_e32 v17, 31, v16
	v_lshlrev_b64 v[26:27], 9, v[26:27]
	v_lshlrev_b64 v[16:17], 9, v[16:17]
	v_lshl_add_u64 v[26:27], v[18:19], 0, v[26:27]
	v_lshl_add_u64 v[16:17], v[18:19], 0, v[16:17]
	global_store_dwordx4 v[26:27], v[28:31], off sc1
	global_store_dwordx4 v[16:17], v[28:31], off sc1

.LBB0_1116:
	s_ashr_i32 s14, s22, 31
	s_lshr_b32 s14, s14, 27
	s_add_i32 s14, s22, s14
	s_ashr_i32 s15, s14, 5
	s_lshl_b32 s14, s15, 6
	s_lshl_b32 s15, s15, 10
	s_andn2_b64 vcc, exec, s[6:7]
	s_sub_i32 s24, 0, s15
	s_cbranch_vccnz .LBB0_1118
	v_or_b32_e32 v50, s14, v20
	s_add_i32 s18, s23, s24
	v_or_b32_e32 v26, 8, v50
	v_or_b32_e32 v30, 16, v50
	s_ashr_i32 s19, s18, 31
	v_ashrrev_i32_e32 v51, 31, v50
	v_ashrrev_i32_e32 v27, 31, v26
	v_ashrrev_i32_e32 v31, 31, v30
	v_lshl_add_u64 v[52:53], s[18:19], 2, v[14:15]
	v_lshlrev_b64 v[16:17], 12, v[50:51]
	v_lshlrev_b64 v[26:27], 12, v[26:27]
	v_lshlrev_b64 v[30:31], 12, v[30:31]
	v_or_b32_e32 v34, 24, v50
	v_lshl_add_u64 v[16:17], v[52:53], 0, v[16:17]
	v_lshl_add_u64 v[26:27], v[52:53], 0, v[26:27]
	v_lshl_add_u64 v[30:31], v[52:53], 0, v[30:31]
	v_ashrrev_i32_e32 v35, 31, v34
	v_or_b32_e32 v38, 32, v50
	global_load_dwordx4 v[16:19], v[16:17], off nt
	v_lshlrev_b64 v[34:35], 12, v[34:35]
	global_load_dwordx4 v[26:29], v[26:27], off nt
	v_ashrrev_i32_e32 v39, 31, v38
	global_load_dwordx4 v[30:33], v[30:31], off nt
	v_lshl_add_u64 v[34:35], v[52:53], 0, v[34:35]
	v_lshlrev_b64 v[38:39], 12, v[38:39]
	v_or_b32_e32 v42, 40, v50
	global_load_dwordx4 v[34:37], v[34:35], off nt
	v_lshl_add_u64 v[38:39], v[52:53], 0, v[38:39]
	v_ashrrev_i32_e32 v43, 31, v42
	global_load_dwordx4 v[38:41], v[38:39], off nt
	v_lshlrev_b64 v[42:43], 12, v[42:43]
	v_or_b32_e32 v46, 48, v50
	v_lshl_add_u64 v[42:43], v[52:53], 0, v[42:43]
	v_ashrrev_i32_e32 v47, 31, v46
	global_load_dwordx4 v[42:45], v[42:43], off nt
	v_lshlrev_b64 v[46:47], 12, v[46:47]
	v_or_b32_e32 v50, 56, v50
	v_lshl_add_u64 v[46:47], v[52:53], 0, v[46:47]
	v_ashrrev_i32_e32 v51, 31, v50
	global_load_dwordx4 v[46:49], v[46:47], off nt
	v_lshlrev_b64 v[50:51], 12, v[50:51]
	v_lshl_add_u64 v[50:51], v[52:53], 0, v[50:51]
	global_load_dwordx4 v[50:53], v[50:51], off nt
	v_add_u32_e32 v11, v21, v23
	v_add_u32_e32 v13, 0x420, v11
	s_ashr_i32 s15, s14, 31
	s_waitcnt vmcnt(7)
	ds_write2_b32 v22, v16, v17 offset1:1
	ds_write2_b32 v22, v18, v19 offset0:2 offset1:3
	s_waitcnt vmcnt(6)
	ds_write2_b32 v11, v26, v27 offset1:1
	ds_write2_b32 v11, v28, v29 offset0:2 offset1:3
	v_lshl_add_u64 v[16:17], s[14:15], 1, v[8:9]
	s_waitcnt vmcnt(5)
	ds_write2_b32 v13, v30, v31 offset1:1
	v_add_u32_e32 v13, 0x428, v11
	ds_write2_b32 v13, v32, v33 offset1:1
	v_add_u32_e32 v13, 0x840, v11
	v_add_u32_e32 v11, 0x848, v11
	s_waitcnt vmcnt(4)
	ds_write2_b32 v11, v36, v37 offset1:1
	v_add_u32_e32 v11, 0x1080, v22
	s_waitcnt vmcnt(3)
	ds_write2_b32 v11, v38, v39 offset1:1
	v_add_u32_e32 v11, 0x1088, v22
	ds_write2_b32 v11, v40, v41 offset1:1
	v_add_u32_e32 v11, 0x14a0, v22
	ds_write2_b32 v13, v34, v35 offset1:1
	s_waitcnt vmcnt(2)
	ds_write2_b32 v11, v42, v43 offset1:1
	v_add_u32_e32 v11, 0x14a8, v22
	ds_write2_b32 v11, v44, v45 offset1:1
	v_add_u32_e32 v11, 0x18c0, v22
	v_add_u32_e32 v44, s18, v0
	s_waitcnt vmcnt(1)
	ds_write2_b32 v11, v46, v47 offset1:1
	v_add_u32_e32 v11, 0x18c8, v22
	ds_write2_b32 v11, v48, v49 offset1:1
	v_add_u32_e32 v11, 0x1ce0, v22
	s_waitcnt vmcnt(0)
	ds_write2_b32 v11, v50, v51 offset1:1
	v_add_u32_e32 v11, 0x1ce8, v22
	ds_write2_b32 v11, v52, v53 offset1:1
	s_waitcnt lgkmcnt(0)
	ds_read2_b32 v[18:19], v24 offset0:33 offset1:41
	ds_read2_b32 v[30:31], v24 offset1:8
	ds_read2_b32 v[32:33], v24 offset0:66 offset1:74
	ds_read2_b32 v[34:35], v24 offset0:99 offset1:107
	ds_read2_b32 v[36:37], v24 offset0:132 offset1:140
	ds_read2_b32 v[38:39], v24 offset0:165 offset1:173
	ds_read2_b32 v[40:41], v24 offset0:198 offset1:206
	ds_read2_b32 v[42:43], v24 offset0:231 offset1:239
	v_ashrrev_i32_e32 v45, 31, v44
	v_lshlrev_b64 v[46:47], 9, v[44:45]
	s_waitcnt lgkmcnt(6)
	v_cvt_pk_bf16_f32 v26, v30, v18
	s_waitcnt lgkmcnt(4)
	v_cvt_pk_bf16_f32 v27, v32, v34
	s_waitcnt lgkmcnt(2)
	v_cvt_pk_bf16_f32 v28, v36, v38
	s_waitcnt lgkmcnt(0)
	v_cvt_pk_bf16_f32 v29, v40, v42
	v_lshl_add_u64 v[46:47], v[16:17], 0, v[46:47]
	v_add_u32_e32 v18, 8, v44
	global_store_dwordx4 v[46:47], v[26:29], off sc1
	v_add_u32_e32 v46, 16, v44
	v_ashrrev_i32_e32 v47, 31, v46
	v_cvt_pk_bf16_f32 v26, v31, v19
	v_ashrrev_i32_e32 v19, 31, v18
	v_lshlrev_b64 v[18:19], 9, v[18:19]
	v_cvt_pk_bf16_f32 v27, v33, v35
	v_cvt_pk_bf16_f32 v28, v37, v39
	v_cvt_pk_bf16_f32 v29, v41, v43
	v_lshl_add_u64 v[18:19], v[16:17], 0, v[18:19]
	global_store_dwordx4 v[18:19], v[26:29], off sc1
	ds_read2_b32 v[18:19], v24 offset0:49 offset1:57
	ds_read2_b32 v[30:31], v24 offset0:16 offset1:24
	ds_read2_b32 v[32:33], v24 offset0:82 offset1:90
	ds_read2_b32 v[34:35], v24 offset0:115 offset1:123
	ds_read2_b32 v[36:37], v24 offset0:148 offset1:156
	ds_read2_b32 v[38:39], v24 offset0:181 offset1:189
	ds_read2_b32 v[40:41], v24 offset0:214 offset1:222
	ds_read2_b32 v[42:43], v24 offset0:247 offset1:255
	v_lshlrev_b64 v[46:47], 9, v[46:47]
	s_waitcnt lgkmcnt(6)
	v_cvt_pk_bf16_f32 v26, v30, v18
	s_waitcnt lgkmcnt(4)
	v_cvt_pk_bf16_f32 v27, v32, v34
	s_waitcnt lgkmcnt(2)
	v_cvt_pk_bf16_f32 v28, v36, v38
	s_waitcnt lgkmcnt(0)
	v_cvt_pk_bf16_f32 v29, v40, v42
	v_lshl_add_u64 v[46:47], v[16:17], 0, v[46:47]
	v_add_u32_e32 v18, 24, v44
	global_store_dwordx4 v[46:47], v[26:29], off sc1
	s_nop 1
	v_cvt_pk_bf16_f32 v26, v31, v19
	v_ashrrev_i32_e32 v19, 31, v18
	v_lshlrev_b64 v[18:19], 9, v[18:19]
	v_cvt_pk_bf16_f32 v27, v33, v35
	v_cvt_pk_bf16_f32 v28, v37, v39
	v_cvt_pk_bf16_f32 v29, v41, v43
	v_lshl_add_u64 v[16:17], v[16:17], 0, v[18:19]
	global_store_dwordx4 v[16:17], v[26:29], off sc1
	s_waitcnt lgkmcnt(0)
	s_cbranch_execnz .LBB0_1115
	s_branch .LBB0_1114

.LBB0_1121:
	s_add_i32 s12, s12, s11
	v_add_u32_e32 v8, s12, v20
	s_ashr_i32 s15, s14, 31
	v_ashrrev_i32_e32 v9, 31, v8
	s_mov_b32 s57, s56
	v_lshl_add_u64 v[14:15], s[14:15], 1, v[6:7]
	v_lshlrev_b64 v[16:17], 9, v[8:9]
	s_mov_b32 s58, s56
	s_mov_b32 s59, s56
	v_mov_b64_e32 v[26:27], s[56:57]
	v_lshl_add_u64 v[16:17], v[14:15], 0, v[16:17]
	v_mov_b64_e32 v[28:29], s[58:59]
	global_store_dwordx4 v[16:17], v[26:29], off sc1
	v_add_u32_e32 v16, 8, v8
	v_ashrrev_i32_e32 v17, 31, v16
	v_lshlrev_b64 v[16:17], 9, v[16:17]
	v_lshl_add_u64 v[16:17], v[14:15], 0, v[16:17]
	global_store_dwordx4 v[16:17], v[26:29], off sc1
	v_add_u32_e32 v16, 16, v8
	v_add_u32_e32 v8, 24, v8
	v_ashrrev_i32_e32 v17, 31, v16
	v_ashrrev_i32_e32 v9, 31, v8
	v_lshlrev_b64 v[16:17], 9, v[16:17]
	v_lshlrev_b64 v[8:9], 9, v[8:9]
	v_lshl_add_u64 v[16:17], v[14:15], 0, v[16:17]
	v_lshl_add_u64 v[8:9], v[14:15], 0, v[8:9]
	global_store_dwordx4 v[16:17], v[26:29], off sc1
	global_store_dwordx4 v[8:9], v[26:29], off sc1

.LBB0_1123:
	s_ashr_i32 s12, s10, 31
	s_lshr_b32 s12, s12, 27
	s_add_i32 s12, s10, s12
	s_ashr_i32 s12, s12, 5
	s_lshl_b32 s14, s12, 6
	s_lshl_b32 s12, s12, 10
	s_andn2_b64 vcc, exec, s[6:7]
	s_sub_i32 s12, 0, s12
	s_cbranch_vccnz .LBB0_1125
	v_or_b32_e32 v8, s14, v20
	s_add_i32 s18, s11, s12
	v_or_b32_e32 v26, 8, v8
	v_or_b32_e32 v30, 16, v8
	s_ashr_i32 s19, s18, 31
	v_ashrrev_i32_e32 v9, 31, v8
	v_ashrrev_i32_e32 v27, 31, v26
	v_ashrrev_i32_e32 v31, 31, v30
	v_lshl_add_u64 v[18:19], s[18:19], 2, v[4:5]
	v_lshlrev_b64 v[14:15], 12, v[8:9]
	v_lshlrev_b64 v[26:27], 12, v[26:27]
	v_lshlrev_b64 v[30:31], 12, v[30:31]
	v_or_b32_e32 v34, 24, v8
	v_lshl_add_u64 v[14:15], v[18:19], 0, v[14:15]
	v_lshl_add_u64 v[26:27], v[18:19], 0, v[26:27]
	v_lshl_add_u64 v[30:31], v[18:19], 0, v[30:31]
	v_ashrrev_i32_e32 v35, 31, v34
	v_or_b32_e32 v38, 32, v8
	global_load_dwordx4 v[14:17], v[14:15], off nt
	v_lshlrev_b64 v[34:35], 12, v[34:35]
	global_load_dwordx4 v[26:29], v[26:27], off nt
	v_ashrrev_i32_e32 v39, 31, v38
	global_load_dwordx4 v[30:33], v[30:31], off nt
	v_lshl_add_u64 v[34:35], v[18:19], 0, v[34:35]
	v_lshlrev_b64 v[38:39], 12, v[38:39]
	v_or_b32_e32 v42, 40, v8
	global_load_dwordx4 v[34:37], v[34:35], off nt
	v_lshl_add_u64 v[38:39], v[18:19], 0, v[38:39]
	v_ashrrev_i32_e32 v43, 31, v42
	global_load_dwordx4 v[38:41], v[38:39], off nt
	v_lshlrev_b64 v[42:43], 12, v[42:43]
	v_or_b32_e32 v46, 48, v8
	v_lshl_add_u64 v[42:43], v[18:19], 0, v[42:43]
	v_ashrrev_i32_e32 v47, 31, v46
	global_load_dwordx4 v[42:45], v[42:43], off nt
	v_lshlrev_b64 v[46:47], 12, v[46:47]
	v_or_b32_e32 v8, 56, v8
	v_lshl_add_u64 v[46:47], v[18:19], 0, v[46:47]
	v_ashrrev_i32_e32 v9, 31, v8
	global_load_dwordx4 v[46:49], v[46:47], off nt
	v_lshlrev_b64 v[8:9], 12, v[8:9]
	v_lshl_add_u64 v[8:9], v[18:19], 0, v[8:9]
	global_load_dwordx4 v[50:53], v[8:9], off nt
	v_add_u32_e32 v0, v21, v23
	v_add_u32_e32 v8, 0x420, v0
	s_ashr_i32 s15, s14, 31
	s_waitcnt vmcnt(7)
	ds_write2_b32 v22, v14, v15 offset1:1
	ds_write2_b32 v22, v16, v17 offset0:2 offset1:3
	s_waitcnt vmcnt(6)
	ds_write2_b32 v0, v26, v27 offset1:1
	ds_write2_b32 v0, v28, v29 offset0:2 offset1:3
	s_waitcnt vmcnt(5)
	ds_write2_b32 v8, v30, v31 offset1:1
	v_add_u32_e32 v8, 0x428, v0
	ds_write2_b32 v8, v32, v33 offset1:1
	v_add_u32_e32 v8, 0x840, v0
	v_add_u32_e32 v0, 0x848, v0
	s_waitcnt vmcnt(4)
	ds_write2_b32 v0, v36, v37 offset1:1
	v_add_u32_e32 v0, 0x1080, v22
	s_waitcnt vmcnt(3)
	ds_write2_b32 v0, v38, v39 offset1:1
	v_add_u32_e32 v0, 0x1088, v22
	ds_write2_b32 v0, v40, v41 offset1:1
	v_add_u32_e32 v0, 0x14a0, v22
	ds_write2_b32 v8, v34, v35 offset1:1
	s_waitcnt vmcnt(2)
	ds_write2_b32 v0, v42, v43 offset1:1
	v_add_u32_e32 v0, 0x14a8, v22
	ds_write2_b32 v0, v44, v45 offset1:1
	v_add_u32_e32 v0, 0x18c0, v22
	v_add_u32_e32 v40, s18, v20
	s_waitcnt vmcnt(1)
	ds_write2_b32 v0, v46, v47 offset1:1
	v_add_u32_e32 v0, 0x18c8, v22
	ds_write2_b32 v0, v48, v49 offset1:1
	v_add_u32_e32 v0, 0x1ce0, v22
	s_waitcnt vmcnt(0)
	ds_write2_b32 v0, v50, v51 offset1:1
	v_add_u32_e32 v0, 0x1ce8, v22
	ds_write2_b32 v0, v52, v53 offset1:1
	s_waitcnt lgkmcnt(0)
	ds_read2_b32 v[18:19], v24 offset0:33 offset1:41
	ds_read2_b32 v[26:27], v24 offset1:8
	ds_read2_b32 v[28:29], v24 offset0:66 offset1:74
	ds_read2_b32 v[30:31], v24 offset0:99 offset1:107
	ds_read2_b32 v[32:33], v24 offset0:132 offset1:140
	ds_read2_b32 v[34:35], v24 offset0:165 offset1:173
	ds_read2_b32 v[36:37], v24 offset0:198 offset1:206
	ds_read2_b32 v[38:39], v24 offset0:231 offset1:239
	v_ashrrev_i32_e32 v41, 31, v40
	v_lshl_add_u64 v[8:9], s[14:15], 1, v[6:7]
	v_lshlrev_b64 v[42:43], 9, v[40:41]
	s_waitcnt lgkmcnt(6)
	v_cvt_pk_bf16_f32 v14, v26, v18
	s_waitcnt lgkmcnt(4)
	v_cvt_pk_bf16_f32 v15, v28, v30
	s_waitcnt lgkmcnt(2)
	v_cvt_pk_bf16_f32 v16, v32, v34
	s_waitcnt lgkmcnt(0)
	v_cvt_pk_bf16_f32 v17, v36, v38
	v_lshl_add_u64 v[42:43], v[8:9], 0, v[42:43]
	v_add_u32_e32 v18, 8, v40
	global_store_dwordx4 v[42:43], v[14:17], off sc1
	v_add_u32_e32 v42, 16, v40
	v_ashrrev_i32_e32 v43, 31, v42
	v_cvt_pk_bf16_f32 v14, v27, v19
	v_ashrrev_i32_e32 v19, 31, v18
	v_lshlrev_b64 v[18:19], 9, v[18:19]
	v_cvt_pk_bf16_f32 v15, v29, v31
	v_cvt_pk_bf16_f32 v16, v33, v35
	v_cvt_pk_bf16_f32 v17, v37, v39
	v_lshl_add_u64 v[18:19], v[8:9], 0, v[18:19]
	global_store_dwordx4 v[18:19], v[14:17], off sc1
	ds_read2_b32 v[18:19], v24 offset0:49 offset1:57
	ds_read2_b32 v[26:27], v24 offset0:16 offset1:24
	ds_read2_b32 v[28:29], v24 offset0:82 offset1:90
	ds_read2_b32 v[30:31], v24 offset0:115 offset1:123
	ds_read2_b32 v[32:33], v24 offset0:148 offset1:156
	ds_read2_b32 v[34:35], v24 offset0:181 offset1:189
	ds_read2_b32 v[36:37], v24 offset0:214 offset1:222
	ds_read2_b32 v[38:39], v24 offset0:247 offset1:255
	v_lshlrev_b64 v[42:43], 9, v[42:43]
	s_waitcnt lgkmcnt(6)
	v_cvt_pk_bf16_f32 v14, v26, v18
	s_waitcnt lgkmcnt(4)
	v_cvt_pk_bf16_f32 v15, v28, v30
	s_waitcnt lgkmcnt(2)
	v_cvt_pk_bf16_f32 v16, v32, v34
	s_waitcnt lgkmcnt(0)
	v_cvt_pk_bf16_f32 v17, v36, v38
	v_lshl_add_u64 v[42:43], v[8:9], 0, v[42:43]
	v_add_u32_e32 v18, 24, v40
	global_store_dwordx4 v[42:43], v[14:17], off sc1
	s_nop 1
	v_cvt_pk_bf16_f32 v14, v27, v19
	v_ashrrev_i32_e32 v19, 31, v18
	v_lshlrev_b64 v[18:19], 9, v[18:19]
	v_cvt_pk_bf16_f32 v15, v29, v31
	v_cvt_pk_bf16_f32 v16, v33, v35
	v_cvt_pk_bf16_f32 v17, v37, v39
	v_lshl_add_u64 v[8:9], v[8:9], 0, v[18:19]
	global_store_dwordx4 v[8:9], v[14:17], off sc1
	s_waitcnt lgkmcnt(0)
	s_cbranch_execnz .LBB0_1122
	s_branch .LBB0_1121

.LBB0_1128:
	s_ashr_i32 s7, s6, 31
	s_lshr_b32 s7, s7, 27
	s_add_i32 s7, s6, s7
	s_ashr_i32 s7, s7, 5
	s_lshl_b32 s10, s7, 6
	s_lshl_b32 s7, s7, 10
	v_subrev_u32_e32 v4, s7, v0
	s_ashr_i32 s11, s10, 31
	v_ashrrev_i32_e32 v5, 31, v4
	s_mov_b32 s57, s56
	v_lshl_add_u64 v[6:7], s[10:11], 1, v[2:3]
	v_lshlrev_b64 v[8:9], 9, v[4:5]
	s_mov_b32 s58, s56
	s_mov_b32 s59, s56
	v_mov_b64_e32 v[14:15], s[56:57]
	v_lshl_add_u64 v[8:9], v[6:7], 0, v[8:9]
	v_mov_b64_e32 v[16:17], s[58:59]
	global_store_dwordx4 v[8:9], v[14:17], off sc1
	v_add_u32_e32 v8, 8, v4
	v_ashrrev_i32_e32 v9, 31, v8
	v_lshlrev_b64 v[8:9], 9, v[8:9]
	v_lshl_add_u64 v[8:9], v[6:7], 0, v[8:9]
	global_store_dwordx4 v[8:9], v[14:17], off sc1
	v_add_u32_e32 v8, 16, v4
	v_add_u32_e32 v4, 24, v4
	v_ashrrev_i32_e32 v9, 31, v8
	v_ashrrev_i32_e32 v5, 31, v4
	v_lshlrev_b64 v[8:9], 9, v[8:9]
	v_lshlrev_b64 v[4:5], 9, v[4:5]
	s_add_i32 s7, s6, 0x200
	v_lshl_add_u64 v[8:9], v[6:7], 0, v[8:9]
	v_lshl_add_u64 v[4:5], v[6:7], 0, v[4:5]
	v_add_u32_e32 v0, 0x4000, v0
	s_cmpk_lt_i32 s6, 0xfe40
	s_mov_b32 s6, s7
	global_store_dwordx4 v[8:9], v[14:17], off sc1
	global_store_dwordx4 v[4:5], v[14:17], off sc1
	s_cbranch_scc1 .LBB0_1128

.LBB0_1130:
	s_add_i32 s10, s10, s9
	v_add_u32_e32 v6, s10, v20
	s_ashr_i32 s15, s14, 31
	v_ashrrev_i32_e32 v7, 31, v6
	s_mov_b32 s57, s56
	v_lshl_add_u64 v[8:9], s[14:15], 1, v[4:5]
	v_lshlrev_b64 v[14:15], 11, v[6:7]
	s_mov_b32 s58, s56
	s_mov_b32 s59, s56
	v_mov_b64_e32 v[16:17], s[56:57]
	v_lshl_add_u64 v[14:15], v[8:9], 0, v[14:15]
	v_mov_b64_e32 v[18:19], s[58:59]
	global_store_dwordx4 v[14:15], v[16:19], off sc1
	v_add_u32_e32 v14, 8, v6
	v_ashrrev_i32_e32 v15, 31, v14
	v_lshlrev_b64 v[14:15], 11, v[14:15]
	v_lshl_add_u64 v[14:15], v[8:9], 0, v[14:15]
	global_store_dwordx4 v[14:15], v[16:19], off sc1
	v_add_u32_e32 v14, 16, v6
	v_add_u32_e32 v6, 24, v6
	v_ashrrev_i32_e32 v15, 31, v14
	v_ashrrev_i32_e32 v7, 31, v6
	v_lshlrev_b64 v[14:15], 11, v[14:15]
	v_lshlrev_b64 v[6:7], 11, v[6:7]
	v_lshl_add_u64 v[14:15], v[8:9], 0, v[14:15]
	v_lshl_add_u64 v[6:7], v[8:9], 0, v[6:7]
	global_store_dwordx4 v[14:15], v[16:19], off sc1
	global_store_dwordx4 v[6:7], v[16:19], off sc1

.LBB0_1132:
	s_ashr_i32 s10, s8, 31
	s_lshr_b32 s10, s10, 27
	s_add_i32 s10, s8, s10
	s_ashr_i32 s10, s10, 5
	s_lshl_b32 s14, s10, 6
	s_lshl_b32 s10, s10, 10
	s_andn2_b64 vcc, exec, s[6:7]
	s_sub_i32 s10, 0, s10
	s_cbranch_vccnz .LBB0_1134
	s_add_i32 s18, s9, s10
	v_or_b32_e32 v18, s14, v20
	s_ashr_i32 s19, s18, 31
	v_ashrrev_i32_e32 v19, 31, v18
	v_or_b32_e32 v14, 8, v18
	v_or_b32_e32 v26, 16, v18
	v_lshl_add_u64 v[46:47], s[18:19], 2, v[2:3]
	v_lshlrev_b64 v[6:7], 12, v[18:19]
	v_ashrrev_i32_e32 v15, 31, v14
	v_ashrrev_i32_e32 v27, 31, v26
	v_lshl_add_u64 v[6:7], v[46:47], 0, v[6:7]
	v_lshlrev_b64 v[14:15], 12, v[14:15]
	v_lshlrev_b64 v[26:27], 12, v[26:27]
	v_or_b32_e32 v30, 24, v18
	global_load_dwordx4 v[6:9], v[6:7], off nt
	v_lshl_add_u64 v[14:15], v[46:47], 0, v[14:15]
	v_lshl_add_u64 v[26:27], v[46:47], 0, v[26:27]
	v_ashrrev_i32_e32 v31, 31, v30
	v_or_b32_e32 v34, 32, v18
	global_load_dwordx4 v[14:17], v[14:15], off nt
	v_lshlrev_b64 v[30:31], 12, v[30:31]
	global_load_dwordx4 v[26:29], v[26:27], off nt
	v_ashrrev_i32_e32 v35, 31, v34
	v_lshl_add_u64 v[30:31], v[46:47], 0, v[30:31]
	v_lshlrev_b64 v[34:35], 12, v[34:35]
	v_or_b32_e32 v38, 40, v18
	global_load_dwordx4 v[30:33], v[30:31], off nt
	v_lshl_add_u64 v[34:35], v[46:47], 0, v[34:35]
	v_ashrrev_i32_e32 v39, 31, v38
	global_load_dwordx4 v[34:37], v[34:35], off nt
	v_lshlrev_b64 v[38:39], 12, v[38:39]
	v_or_b32_e32 v42, 48, v18
	v_lshl_add_u64 v[38:39], v[46:47], 0, v[38:39]
	v_ashrrev_i32_e32 v43, 31, v42
	global_load_dwordx4 v[38:41], v[38:39], off nt
	v_lshlrev_b64 v[42:43], 12, v[42:43]
	v_or_b32_e32 v18, 56, v18
	v_lshl_add_u64 v[42:43], v[46:47], 0, v[42:43]
	v_ashrrev_i32_e32 v19, 31, v18
	global_load_dwordx4 v[42:45], v[42:43], off nt
	v_lshlrev_b64 v[18:19], 12, v[18:19]
	v_lshl_add_u64 v[18:19], v[46:47], 0, v[18:19]
	global_load_dwordx4 v[46:49], v[18:19], off nt
	v_add_u32_e32 v0, v21, v23
	s_ashr_i32 s15, s14, 31
	s_waitcnt vmcnt(7)
	ds_write2_b32 v22, v6, v7 offset1:1
	ds_write2_b32 v22, v8, v9 offset0:2 offset1:3
	v_add_u32_e32 v6, 0x420, v0
	s_waitcnt vmcnt(6)
	ds_write2_b32 v0, v14, v15 offset1:1
	ds_write2_b32 v0, v16, v17 offset0:2 offset1:3
	s_waitcnt vmcnt(5)
	ds_write2_b32 v6, v26, v27 offset1:1
	v_add_u32_e32 v6, 0x428, v0
	ds_write2_b32 v6, v28, v29 offset1:1
	v_add_u32_e32 v6, 0x840, v0
	v_add_u32_e32 v0, 0x848, v0
	s_waitcnt vmcnt(4)
	ds_write2_b32 v0, v32, v33 offset1:1
	v_add_u32_e32 v0, 0x1080, v22
	ds_write2_b32 v6, v30, v31 offset1:1
	s_waitcnt vmcnt(3)
	ds_write2_b32 v0, v34, v35 offset1:1
	v_add_u32_e32 v0, 0x1088, v22
	ds_write2_b32 v0, v36, v37 offset1:1
	v_add_u32_e32 v0, 0x14a0, v22
	v_lshl_add_u64 v[6:7], s[14:15], 1, v[4:5]
	s_waitcnt vmcnt(2)
	ds_write2_b32 v0, v38, v39 offset1:1
	v_add_u32_e32 v0, 0x14a8, v22
	ds_write2_b32 v0, v40, v41 offset1:1
	v_add_u32_e32 v0, 0x18c0, v22
	v_add_u32_e32 v38, s18, v20
	s_waitcnt vmcnt(1)
	ds_write2_b32 v0, v42, v43 offset1:1
	v_add_u32_e32 v0, 0x18c8, v22
	ds_write2_b32 v0, v44, v45 offset1:1
	v_add_u32_e32 v0, 0x1ce0, v22
	s_waitcnt vmcnt(0)
	ds_write2_b32 v0, v46, v47 offset1:1
	v_add_u32_e32 v0, 0x1ce8, v22
	ds_write2_b32 v0, v48, v49 offset1:1
	s_waitcnt lgkmcnt(0)
	ds_read2_b32 v[8:9], v24 offset0:33 offset1:41
	ds_read2_b32 v[18:19], v24 offset1:8
	ds_read2_b32 v[26:27], v24 offset0:66 offset1:74
	ds_read2_b32 v[28:29], v24 offset0:99 offset1:107
	ds_read2_b32 v[30:31], v24 offset0:132 offset1:140
	ds_read2_b32 v[32:33], v24 offset0:165 offset1:173
	ds_read2_b32 v[34:35], v24 offset0:198 offset1:206
	ds_read2_b32 v[36:37], v24 offset0:231 offset1:239
	v_ashrrev_i32_e32 v39, 31, v38
	v_lshlrev_b64 v[40:41], 11, v[38:39]
	s_waitcnt lgkmcnt(6)
	v_cvt_pk_bf16_f32 v14, v18, v8
	s_waitcnt lgkmcnt(4)
	v_cvt_pk_bf16_f32 v15, v26, v28
	s_waitcnt lgkmcnt(2)
	v_cvt_pk_bf16_f32 v16, v30, v32
	s_waitcnt lgkmcnt(0)
	v_cvt_pk_bf16_f32 v17, v34, v36
	v_lshl_add_u64 v[40:41], v[6:7], 0, v[40:41]
	v_add_u32_e32 v8, 8, v38
	global_store_dwordx4 v[40:41], v[14:17], off sc1
	v_add_u32_e32 v40, 16, v38
	v_ashrrev_i32_e32 v41, 31, v40
	v_cvt_pk_bf16_f32 v14, v19, v9
	v_ashrrev_i32_e32 v9, 31, v8
	v_lshlrev_b64 v[8:9], 11, v[8:9]
	v_cvt_pk_bf16_f32 v15, v27, v29
	v_cvt_pk_bf16_f32 v16, v31, v33
	v_cvt_pk_bf16_f32 v17, v35, v37
	v_lshl_add_u64 v[8:9], v[6:7], 0, v[8:9]
	global_store_dwordx4 v[8:9], v[14:17], off sc1
	ds_read2_b32 v[8:9], v24 offset0:49 offset1:57
	ds_read2_b32 v[18:19], v24 offset0:16 offset1:24
	ds_read2_b32 v[26:27], v24 offset0:82 offset1:90
	ds_read2_b32 v[28:29], v24 offset0:115 offset1:123
	ds_read2_b32 v[30:31], v24 offset0:148 offset1:156
	ds_read2_b32 v[32:33], v24 offset0:181 offset1:189
	ds_read2_b32 v[34:35], v24 offset0:214 offset1:222
	ds_read2_b32 v[36:37], v24 offset0:247 offset1:255
	v_lshlrev_b64 v[40:41], 11, v[40:41]
	s_waitcnt lgkmcnt(6)
	v_cvt_pk_bf16_f32 v14, v18, v8
	s_waitcnt lgkmcnt(4)
	v_cvt_pk_bf16_f32 v15, v26, v28
	s_waitcnt lgkmcnt(2)
	v_cvt_pk_bf16_f32 v16, v30, v32
	s_waitcnt lgkmcnt(0)
	v_cvt_pk_bf16_f32 v17, v34, v36
	v_lshl_add_u64 v[40:41], v[6:7], 0, v[40:41]
	v_add_u32_e32 v8, 24, v38
	global_store_dwordx4 v[40:41], v[14:17], off sc1
	s_nop 1
	v_cvt_pk_bf16_f32 v14, v19, v9
	v_ashrrev_i32_e32 v9, 31, v8
	v_lshlrev_b64 v[8:9], 11, v[8:9]
	v_cvt_pk_bf16_f32 v15, v27, v29
	v_cvt_pk_bf16_f32 v16, v31, v33
	v_cvt_pk_bf16_f32 v17, v35, v37
	v_lshl_add_u64 v[6:7], v[6:7], 0, v[8:9]
	global_store_dwordx4 v[6:7], v[14:17], off sc1
	s_waitcnt lgkmcnt(0)
	s_cbranch_execnz .LBB0_1131
	s_branch .LBB0_1130

.LBB0_1137:
	s_add_i32 s10, s10, s8
	v_add_u32_e32 v6, s10, v20
	s_ashr_i32 s15, s14, 31
	v_ashrrev_i32_e32 v7, 31, v6
	s_mov_b32 s57, s56
	v_lshl_add_u64 v[8:9], s[14:15], 1, v[4:5]
	v_lshlrev_b64 v[14:15], 11, v[6:7]
	s_mov_b32 s58, s56
	s_mov_b32 s59, s56
	v_mov_b64_e32 v[16:17], s[56:57]
	v_lshl_add_u64 v[14:15], v[8:9], 0, v[14:15]
	v_mov_b64_e32 v[18:19], s[58:59]
	global_store_dwordx4 v[14:15], v[16:19], off sc1
	v_add_u32_e32 v14, 8, v6
	v_ashrrev_i32_e32 v15, 31, v14
	v_lshlrev_b64 v[14:15], 11, v[14:15]
	v_lshl_add_u64 v[14:15], v[8:9], 0, v[14:15]
	global_store_dwordx4 v[14:15], v[16:19], off sc1
	v_add_u32_e32 v14, 16, v6
	v_add_u32_e32 v6, 24, v6
	v_ashrrev_i32_e32 v15, 31, v14
	v_ashrrev_i32_e32 v7, 31, v6
	v_lshlrev_b64 v[14:15], 11, v[14:15]
	v_lshlrev_b64 v[6:7], 11, v[6:7]
	v_lshl_add_u64 v[14:15], v[8:9], 0, v[14:15]
	v_lshl_add_u64 v[6:7], v[8:9], 0, v[6:7]
	global_store_dwordx4 v[14:15], v[16:19], off sc1
	global_store_dwordx4 v[6:7], v[16:19], off sc1

.LBB0_1139:
	s_mul_hi_i32 s10, s9, 0x2aaaaaab
	s_lshr_b32 s11, s10, 31
	s_ashr_i32 s10, s10, 4
	s_add_i32 s10, s10, s11
	s_lshl_b32 s14, s10, 6
	s_andn2_b64 vcc, exec, s[6:7]
	s_mulk_i32 s10, 0xf400
	s_cbranch_vccnz .LBB0_1141
	s_add_i32 s18, s8, s10
	v_or_b32_e32 v0, s14, v20
	s_ashr_i32 s19, s18, 31
	v_lshl_add_u64 v[18:19], s[18:19], 2, v[2:3]
	s_movk_i32 s11, 0x3000
	v_or_b32_e32 v11, 8, v0
	v_mad_i64_i32 v[6:7], s[12:13], v0, s11, v[18:19]
	v_mad_i64_i32 v[14:15], s[12:13], v11, s11, v[18:19]
	v_or_b32_e32 v11, 16, v0
	global_load_dwordx4 v[6:9], v[6:7], off nt
	v_mad_i64_i32 v[26:27], s[12:13], v11, s11, v[18:19]
	global_load_dwordx4 v[14:17], v[14:15], off nt
	v_or_b32_e32 v11, 24, v0
	global_load_dwordx4 v[26:29], v[26:27], off nt
	v_mad_i64_i32 v[30:31], s[12:13], v11, s11, v[18:19]
	v_or_b32_e32 v11, 32, v0
	global_load_dwordx4 v[30:33], v[30:31], off nt
	v_mad_i64_i32 v[34:35], s[12:13], v11, s11, v[18:19]
	global_load_dwordx4 v[34:37], v[34:35], off nt
	v_or_b32_e32 v11, 40, v0
	v_mad_i64_i32 v[38:39], s[12:13], v11, s11, v[18:19]
	global_load_dwordx4 v[38:41], v[38:39], off nt
	v_or_b32_e32 v11, 48, v0
	v_mad_i64_i32 v[42:43], s[12:13], v11, s11, v[18:19]
	global_load_dwordx4 v[42:45], v[42:43], off nt
	v_or_b32_e32 v0, 56, v0
	v_mad_i64_i32 v[18:19], s[12:13], v0, s11, v[18:19]
	global_load_dwordx4 v[46:49], v[18:19], off nt
	v_add_u32_e32 v0, v21, v23
	s_ashr_i32 s15, s14, 31
	s_waitcnt vmcnt(7)
	ds_write2_b32 v22, v6, v7 offset1:1
	ds_write2_b32 v22, v8, v9 offset0:2 offset1:3
	v_add_u32_e32 v6, 0x420, v0
	s_waitcnt vmcnt(6)
	ds_write2_b32 v0, v14, v15 offset1:1
	ds_write2_b32 v0, v16, v17 offset0:2 offset1:3
	v_add_u32_e32 v8, s18, v20
	s_waitcnt vmcnt(5)
	ds_write2_b32 v6, v26, v27 offset1:1
	v_add_u32_e32 v6, 0x428, v0
	ds_write2_b32 v6, v28, v29 offset1:1
	v_add_u32_e32 v6, 0x840, v0
	v_add_u32_e32 v0, 0x848, v0
	s_waitcnt vmcnt(4)
	ds_write2_b32 v0, v32, v33 offset1:1
	v_add_u32_e32 v0, 0x1080, v22
	s_waitcnt vmcnt(3)
	ds_write2_b32 v0, v34, v35 offset1:1
	v_add_u32_e32 v0, 0x1088, v22
	ds_write2_b32 v0, v36, v37 offset1:1
	v_add_u32_e32 v0, 0x14a0, v22
	s_waitcnt vmcnt(2)
	ds_write2_b32 v0, v38, v39 offset1:1
	v_add_u32_e32 v0, 0x14a8, v22
	ds_write2_b32 v0, v40, v41 offset1:1
	v_add_u32_e32 v0, 0x18c0, v22
	s_waitcnt vmcnt(1)
	ds_write2_b32 v0, v42, v43 offset1:1
	v_add_u32_e32 v0, 0x18c8, v22
	ds_write2_b32 v0, v44, v45 offset1:1
	v_add_u32_e32 v0, 0x1ce0, v22
	s_waitcnt vmcnt(0)
	ds_write2_b32 v0, v46, v47 offset1:1
	v_add_u32_e32 v0, 0x1ce8, v22
	ds_write2_b32 v6, v30, v31 offset1:1
	ds_write2_b32 v0, v48, v49 offset1:1
	s_waitcnt lgkmcnt(0)
	ds_read2_b32 v[18:19], v24 offset0:33 offset1:41
	ds_read2_b32 v[26:27], v24 offset1:8
	ds_read2_b32 v[28:29], v24 offset0:66 offset1:74
	ds_read2_b32 v[30:31], v24 offset0:99 offset1:107
	ds_read2_b32 v[32:33], v24 offset0:132 offset1:140
	ds_read2_b32 v[34:35], v24 offset0:165 offset1:173
	ds_read2_b32 v[36:37], v24 offset0:198 offset1:206
	ds_read2_b32 v[38:39], v24 offset0:231 offset1:239
	v_ashrrev_i32_e32 v9, 31, v8
	v_lshl_add_u64 v[6:7], s[14:15], 1, v[4:5]
	v_lshlrev_b64 v[40:41], 11, v[8:9]
	s_waitcnt lgkmcnt(6)
	v_cvt_pk_bf16_f32 v14, v26, v18
	s_waitcnt lgkmcnt(4)
	v_cvt_pk_bf16_f32 v15, v28, v30
	s_waitcnt lgkmcnt(2)
	v_cvt_pk_bf16_f32 v16, v32, v34
	s_waitcnt lgkmcnt(0)
	v_cvt_pk_bf16_f32 v17, v36, v38
	v_lshl_add_u64 v[40:41], v[6:7], 0, v[40:41]
	v_add_u32_e32 v18, 8, v8
	global_store_dwordx4 v[40:41], v[14:17], off sc1
	v_add_u32_e32 v40, 16, v8
	v_ashrrev_i32_e32 v41, 31, v40
	v_cvt_pk_bf16_f32 v14, v27, v19
	v_ashrrev_i32_e32 v19, 31, v18
	v_lshlrev_b64 v[18:19], 11, v[18:19]
	v_cvt_pk_bf16_f32 v15, v29, v31
	v_cvt_pk_bf16_f32 v16, v33, v35
	v_cvt_pk_bf16_f32 v17, v37, v39
	v_lshl_add_u64 v[18:19], v[6:7], 0, v[18:19]
	global_store_dwordx4 v[18:19], v[14:17], off sc1
	ds_read2_b32 v[18:19], v24 offset0:49 offset1:57
	ds_read2_b32 v[26:27], v24 offset0:16 offset1:24
	ds_read2_b32 v[28:29], v24 offset0:82 offset1:90
	ds_read2_b32 v[30:31], v24 offset0:115 offset1:123
	ds_read2_b32 v[32:33], v24 offset0:148 offset1:156
	ds_read2_b32 v[34:35], v24 offset0:181 offset1:189
	ds_read2_b32 v[36:37], v24 offset0:214 offset1:222
	ds_read2_b32 v[38:39], v24 offset0:247 offset1:255
	v_add_u32_e32 v8, 24, v8
	v_lshlrev_b64 v[40:41], 11, v[40:41]
	v_ashrrev_i32_e32 v9, 31, v8
	s_waitcnt lgkmcnt(6)
	v_cvt_pk_bf16_f32 v14, v26, v18
	s_waitcnt lgkmcnt(4)
	v_cvt_pk_bf16_f32 v15, v28, v30
	s_waitcnt lgkmcnt(2)
	v_cvt_pk_bf16_f32 v16, v32, v34
	s_waitcnt lgkmcnt(0)
	v_cvt_pk_bf16_f32 v17, v36, v38
	v_lshl_add_u64 v[40:41], v[6:7], 0, v[40:41]
	v_lshlrev_b64 v[8:9], 11, v[8:9]
	global_store_dwordx4 v[40:41], v[14:17], off sc1
	v_lshl_add_u64 v[6:7], v[6:7], 0, v[8:9]
	s_nop 0
	v_cvt_pk_bf16_f32 v14, v27, v19
	v_cvt_pk_bf16_f32 v15, v29, v31
	v_cvt_pk_bf16_f32 v16, v33, v35
	v_cvt_pk_bf16_f32 v17, v37, v39
	global_store_dwordx4 v[6:7], v[14:17], off sc1
	s_waitcnt lgkmcnt(0)
	s_cbranch_execnz .LBB0_1138
	s_branch .LBB0_1137

.LBB0_1143:
	s_add_i32 s9, s9, s5
	v_add_u32_e32 v6, s9, v20
	s_ashr_i32 s15, s14, 31
	v_ashrrev_i32_e32 v7, 31, v6
	s_mov_b32 s57, s56
	v_lshl_add_u64 v[8:9], s[14:15], 1, v[4:5]
	v_lshlrev_b64 v[14:15], 11, v[6:7]
	s_mov_b32 s58, s56
	s_mov_b32 s59, s56
	v_mov_b64_e32 v[16:17], s[56:57]
	v_lshl_add_u64 v[14:15], v[8:9], 0, v[14:15]
	v_mov_b64_e32 v[18:19], s[58:59]
	global_store_dwordx4 v[14:15], v[16:19], off sc1
	v_add_u32_e32 v14, 8, v6
	v_ashrrev_i32_e32 v15, 31, v14
	v_lshlrev_b64 v[14:15], 11, v[14:15]
	v_lshl_add_u64 v[14:15], v[8:9], 0, v[14:15]
	global_store_dwordx4 v[14:15], v[16:19], off sc1
	v_add_u32_e32 v14, 16, v6
	v_add_u32_e32 v6, 24, v6
	v_ashrrev_i32_e32 v15, 31, v14
	v_ashrrev_i32_e32 v7, 31, v6
	v_lshlrev_b64 v[14:15], 11, v[14:15]
	v_lshlrev_b64 v[6:7], 11, v[6:7]
	v_lshl_add_u64 v[14:15], v[8:9], 0, v[14:15]
	v_lshl_add_u64 v[6:7], v[8:9], 0, v[6:7]
	global_store_dwordx4 v[14:15], v[16:19], off sc1
	global_store_dwordx4 v[6:7], v[16:19], off sc1

.LBB0_1145:
	s_ashr_i32 s9, s8, 31
	s_lshr_b32 s9, s9, 27
	s_add_i32 s9, s8, s9
	s_ashr_i32 s9, s9, 5
	s_lshl_b32 s14, s9, 6
	s_lshl_b32 s9, s9, 10
	s_andn2_b64 vcc, exec, s[6:7]
	s_sub_i32 s9, 0, s9
	s_cbranch_vccnz .LBB0_1147
	s_add_i32 s18, s5, s9
	v_or_b32_e32 v18, s14, v20
	s_ashr_i32 s19, s18, 31
	v_ashrrev_i32_e32 v19, 31, v18
	v_or_b32_e32 v14, 8, v18
	v_or_b32_e32 v26, 16, v18
	v_lshl_add_u64 v[46:47], s[18:19], 2, v[2:3]
	v_lshlrev_b64 v[6:7], 12, v[18:19]
	v_ashrrev_i32_e32 v15, 31, v14
	v_ashrrev_i32_e32 v27, 31, v26
	v_lshl_add_u64 v[6:7], v[46:47], 0, v[6:7]
	v_lshlrev_b64 v[14:15], 12, v[14:15]
	v_lshlrev_b64 v[26:27], 12, v[26:27]
	v_or_b32_e32 v30, 24, v18
	global_load_dwordx4 v[6:9], v[6:7], off nt
	v_lshl_add_u64 v[14:15], v[46:47], 0, v[14:15]
	v_lshl_add_u64 v[26:27], v[46:47], 0, v[26:27]
	v_ashrrev_i32_e32 v31, 31, v30
	v_or_b32_e32 v34, 32, v18
	global_load_dwordx4 v[14:17], v[14:15], off nt
	v_lshlrev_b64 v[30:31], 12, v[30:31]
	global_load_dwordx4 v[26:29], v[26:27], off nt
	v_ashrrev_i32_e32 v35, 31, v34
	v_lshl_add_u64 v[30:31], v[46:47], 0, v[30:31]
	v_lshlrev_b64 v[34:35], 12, v[34:35]
	v_or_b32_e32 v38, 40, v18
	global_load_dwordx4 v[30:33], v[30:31], off nt
	v_lshl_add_u64 v[34:35], v[46:47], 0, v[34:35]
	v_ashrrev_i32_e32 v39, 31, v38
	global_load_dwordx4 v[34:37], v[34:35], off nt
	v_lshlrev_b64 v[38:39], 12, v[38:39]
	v_or_b32_e32 v42, 48, v18
	v_lshl_add_u64 v[38:39], v[46:47], 0, v[38:39]
	v_ashrrev_i32_e32 v43, 31, v42
	global_load_dwordx4 v[38:41], v[38:39], off nt
	v_lshlrev_b64 v[42:43], 12, v[42:43]
	v_or_b32_e32 v18, 56, v18
	v_lshl_add_u64 v[42:43], v[46:47], 0, v[42:43]
	v_ashrrev_i32_e32 v19, 31, v18
	global_load_dwordx4 v[42:45], v[42:43], off nt
	v_lshlrev_b64 v[18:19], 12, v[18:19]
	v_lshl_add_u64 v[18:19], v[46:47], 0, v[18:19]
	global_load_dwordx4 v[46:49], v[18:19], off nt
	v_add_u32_e32 v0, v21, v23
	s_ashr_i32 s15, s14, 31
	s_waitcnt vmcnt(7)
	ds_write2_b32 v22, v6, v7 offset1:1
	ds_write2_b32 v22, v8, v9 offset0:2 offset1:3
	v_add_u32_e32 v6, 0x420, v0
	s_waitcnt vmcnt(6)
	ds_write2_b32 v0, v14, v15 offset1:1
	ds_write2_b32 v0, v16, v17 offset0:2 offset1:3
	s_waitcnt vmcnt(5)
	ds_write2_b32 v6, v26, v27 offset1:1
	v_add_u32_e32 v6, 0x428, v0
	ds_write2_b32 v6, v28, v29 offset1:1
	v_add_u32_e32 v6, 0x840, v0
	v_add_u32_e32 v0, 0x848, v0
	s_waitcnt vmcnt(4)
	ds_write2_b32 v0, v32, v33 offset1:1
	v_add_u32_e32 v0, 0x1080, v22
	ds_write2_b32 v6, v30, v31 offset1:1
	s_waitcnt vmcnt(3)
	ds_write2_b32 v0, v34, v35 offset1:1
	v_add_u32_e32 v0, 0x1088, v22
	ds_write2_b32 v0, v36, v37 offset1:1
	v_add_u32_e32 v0, 0x14a0, v22
	v_lshl_add_u64 v[6:7], s[14:15], 1, v[4:5]
	s_waitcnt vmcnt(2)
	ds_write2_b32 v0, v38, v39 offset1:1
	v_add_u32_e32 v0, 0x14a8, v22
	ds_write2_b32 v0, v40, v41 offset1:1
	v_add_u32_e32 v0, 0x18c0, v22
	v_add_u32_e32 v38, s18, v20
	s_waitcnt vmcnt(1)
	ds_write2_b32 v0, v42, v43 offset1:1
	v_add_u32_e32 v0, 0x18c8, v22
	ds_write2_b32 v0, v44, v45 offset1:1
	v_add_u32_e32 v0, 0x1ce0, v22
	s_waitcnt vmcnt(0)
	ds_write2_b32 v0, v46, v47 offset1:1
	v_add_u32_e32 v0, 0x1ce8, v22
	ds_write2_b32 v0, v48, v49 offset1:1
	s_waitcnt lgkmcnt(0)
	ds_read2_b32 v[8:9], v24 offset0:33 offset1:41
	ds_read2_b32 v[18:19], v24 offset1:8
	ds_read2_b32 v[26:27], v24 offset0:66 offset1:74
	ds_read2_b32 v[28:29], v24 offset0:99 offset1:107
	ds_read2_b32 v[30:31], v24 offset0:132 offset1:140
	ds_read2_b32 v[32:33], v24 offset0:165 offset1:173
	ds_read2_b32 v[34:35], v24 offset0:198 offset1:206
	ds_read2_b32 v[36:37], v24 offset0:231 offset1:239
	v_ashrrev_i32_e32 v39, 31, v38
	v_lshlrev_b64 v[40:41], 11, v[38:39]
	s_waitcnt lgkmcnt(6)
	v_cvt_pk_bf16_f32 v14, v18, v8
	s_waitcnt lgkmcnt(4)
	v_cvt_pk_bf16_f32 v15, v26, v28
	s_waitcnt lgkmcnt(2)
	v_cvt_pk_bf16_f32 v16, v30, v32
	s_waitcnt lgkmcnt(0)
	v_cvt_pk_bf16_f32 v17, v34, v36
	v_lshl_add_u64 v[40:41], v[6:7], 0, v[40:41]
	v_add_u32_e32 v8, 8, v38
	global_store_dwordx4 v[40:41], v[14:17], off sc1
	v_add_u32_e32 v40, 16, v38
	v_ashrrev_i32_e32 v41, 31, v40
	v_cvt_pk_bf16_f32 v14, v19, v9
	v_ashrrev_i32_e32 v9, 31, v8
	v_lshlrev_b64 v[8:9], 11, v[8:9]
	v_cvt_pk_bf16_f32 v15, v27, v29
	v_cvt_pk_bf16_f32 v16, v31, v33
	v_cvt_pk_bf16_f32 v17, v35, v37
	v_lshl_add_u64 v[8:9], v[6:7], 0, v[8:9]
	global_store_dwordx4 v[8:9], v[14:17], off sc1
	ds_read2_b32 v[8:9], v24 offset0:49 offset1:57
	ds_read2_b32 v[18:19], v24 offset0:16 offset1:24
	ds_read2_b32 v[26:27], v24 offset0:82 offset1:90
	ds_read2_b32 v[28:29], v24 offset0:115 offset1:123
	ds_read2_b32 v[30:31], v24 offset0:148 offset1:156
	ds_read2_b32 v[32:33], v24 offset0:181 offset1:189
	ds_read2_b32 v[34:35], v24 offset0:214 offset1:222
	ds_read2_b32 v[36:37], v24 offset0:247 offset1:255
	v_lshlrev_b64 v[40:41], 11, v[40:41]
	s_waitcnt lgkmcnt(6)
	v_cvt_pk_bf16_f32 v14, v18, v8
	s_waitcnt lgkmcnt(4)
	v_cvt_pk_bf16_f32 v15, v26, v28
	s_waitcnt lgkmcnt(2)
	v_cvt_pk_bf16_f32 v16, v30, v32
	s_waitcnt lgkmcnt(0)
	v_cvt_pk_bf16_f32 v17, v34, v36
	v_lshl_add_u64 v[40:41], v[6:7], 0, v[40:41]
	v_add_u32_e32 v8, 24, v38
	global_store_dwordx4 v[40:41], v[14:17], off sc1
	s_nop 1
	v_cvt_pk_bf16_f32 v14, v19, v9
	v_ashrrev_i32_e32 v9, 31, v8
	v_lshlrev_b64 v[8:9], 11, v[8:9]
	v_cvt_pk_bf16_f32 v15, v27, v29
	v_cvt_pk_bf16_f32 v16, v31, v33
	v_cvt_pk_bf16_f32 v17, v35, v37
	v_lshl_add_u64 v[6:7], v[6:7], 0, v[8:9]
	global_store_dwordx4 v[6:7], v[14:17], off sc1
	s_waitcnt lgkmcnt(0)
	s_cbranch_execnz .LBB0_1144
	s_branch .LBB0_1143

.LBB0_1151:
	s_add_i32 s8, s8, s5
	v_add_u32_e32 v6, s8, v20
	s_ashr_i32 s7, s6, 31
	v_ashrrev_i32_e32 v7, 31, v6
	s_mov_b32 s57, s56
	v_lshl_add_u64 v[8:9], s[6:7], 1, v[4:5]
	v_lshlrev_b64 v[10:11], 11, v[6:7]
	s_mov_b32 s58, s56
	s_mov_b32 s59, s56
	v_mov_b64_e32 v[12:13], s[56:57]
	v_lshl_add_u64 v[10:11], v[8:9], 0, v[10:11]
	v_mov_b64_e32 v[14:15], s[58:59]
	global_store_dwordx4 v[10:11], v[12:15], off sc1
	v_add_u32_e32 v10, 8, v6
	v_ashrrev_i32_e32 v11, 31, v10
	v_lshlrev_b64 v[10:11], 11, v[10:11]
	v_lshl_add_u64 v[10:11], v[8:9], 0, v[10:11]
	global_store_dwordx4 v[10:11], v[12:15], off sc1
	v_add_u32_e32 v10, 16, v6
	v_add_u32_e32 v6, 24, v6
	v_ashrrev_i32_e32 v11, 31, v10
	v_ashrrev_i32_e32 v7, 31, v6
	v_lshlrev_b64 v[10:11], 11, v[10:11]
	v_lshlrev_b64 v[6:7], 11, v[6:7]
	v_lshl_add_u64 v[10:11], v[8:9], 0, v[10:11]
	v_lshl_add_u64 v[6:7], v[8:9], 0, v[6:7]
	global_store_dwordx4 v[10:11], v[12:15], off sc1
	global_store_dwordx4 v[6:7], v[12:15], off sc1

.LBB0_1153:
	s_ashr_i32 s6, s3, 31
	s_lshr_b32 s6, s6, 25
	s_add_i32 s6, s3, s6
	s_ashr_i32 s7, s6, 7
	s_lshl_b32 s6, s7, 6
	s_lshl_b32 s7, s7, 12
	s_andn2_b64 vcc, exec, s[0:1]
	s_sub_i32 s8, 0, s7
	s_cbranch_vccnz .LBB0_1155
	s_add_i32 s14, s5, s8
	v_or_b32_e32 v18, s6, v20
	s_ashr_i32 s15, s14, 31
	v_ashrrev_i32_e32 v19, 31, v18
	v_or_b32_e32 v10, 8, v18
	v_or_b32_e32 v14, 16, v18
	v_lshl_add_u64 v[42:43], s[14:15], 2, v[2:3]
	v_lshlrev_b64 v[6:7], 14, v[18:19]
	v_ashrrev_i32_e32 v11, 31, v10
	v_ashrrev_i32_e32 v15, 31, v14
	v_lshl_add_u64 v[6:7], v[42:43], 0, v[6:7]
	v_lshlrev_b64 v[10:11], 14, v[10:11]
	v_lshlrev_b64 v[14:15], 14, v[14:15]
	v_or_b32_e32 v26, 24, v18
	global_load_dwordx4 v[6:9], v[6:7], off nt
	v_lshl_add_u64 v[10:11], v[42:43], 0, v[10:11]
	v_lshl_add_u64 v[14:15], v[42:43], 0, v[14:15]
	v_ashrrev_i32_e32 v27, 31, v26
	v_or_b32_e32 v30, 32, v18
	global_load_dwordx4 v[10:13], v[10:11], off nt
	v_lshlrev_b64 v[26:27], 14, v[26:27]
	global_load_dwordx4 v[14:17], v[14:15], off nt
	v_ashrrev_i32_e32 v31, 31, v30
	v_lshl_add_u64 v[26:27], v[42:43], 0, v[26:27]
	v_lshlrev_b64 v[30:31], 14, v[30:31]
	v_or_b32_e32 v34, 40, v18
	global_load_dwordx4 v[26:29], v[26:27], off nt
	v_lshl_add_u64 v[30:31], v[42:43], 0, v[30:31]
	v_ashrrev_i32_e32 v35, 31, v34
	global_load_dwordx4 v[30:33], v[30:31], off nt
	v_lshlrev_b64 v[34:35], 14, v[34:35]
	v_or_b32_e32 v38, 48, v18
	v_lshl_add_u64 v[34:35], v[42:43], 0, v[34:35]
	v_ashrrev_i32_e32 v39, 31, v38
	global_load_dwordx4 v[34:37], v[34:35], off nt
	v_lshlrev_b64 v[38:39], 14, v[38:39]
	v_or_b32_e32 v18, 56, v18
	v_lshl_add_u64 v[38:39], v[42:43], 0, v[38:39]
	v_ashrrev_i32_e32 v19, 31, v18
	global_load_dwordx4 v[38:41], v[38:39], off nt
	v_lshlrev_b64 v[18:19], 14, v[18:19]
	v_lshl_add_u64 v[18:19], v[42:43], 0, v[18:19]
	global_load_dwordx4 v[42:45], v[18:19], off nt
	v_add_u32_e32 v0, v21, v23
	s_ashr_i32 s7, s6, 31
	s_waitcnt vmcnt(7)
	ds_write2_b32 v22, v6, v7 offset1:1
	ds_write2_b32 v22, v8, v9 offset0:2 offset1:3
	v_add_u32_e32 v6, 0x420, v0
	s_waitcnt vmcnt(6)
	ds_write2_b32 v0, v10, v11 offset1:1
	ds_write2_b32 v0, v12, v13 offset0:2 offset1:3
	s_waitcnt vmcnt(5)
	ds_write2_b32 v6, v14, v15 offset1:1
	v_add_u32_e32 v6, 0x428, v0
	ds_write2_b32 v6, v16, v17 offset1:1
	v_add_u32_e32 v6, 0x840, v0
	v_add_u32_e32 v0, 0x848, v0
	s_waitcnt vmcnt(4)
	ds_write2_b32 v0, v28, v29 offset1:1
	v_add_u32_e32 v0, 0x1080, v22
	ds_write2_b32 v6, v26, v27 offset1:1
	s_waitcnt vmcnt(3)
	ds_write2_b32 v0, v30, v31 offset1:1
	v_add_u32_e32 v0, 0x1088, v22
	ds_write2_b32 v0, v32, v33 offset1:1
	v_add_u32_e32 v0, 0x14a0, v22
	v_lshl_add_u64 v[6:7], s[6:7], 1, v[4:5]
	s_waitcnt vmcnt(2)
	ds_write2_b32 v0, v34, v35 offset1:1
	v_add_u32_e32 v0, 0x14a8, v22
	ds_write2_b32 v0, v36, v37 offset1:1
	v_add_u32_e32 v0, 0x18c0, v22
	v_add_u32_e32 v34, s14, v20
	s_waitcnt vmcnt(1)
	ds_write2_b32 v0, v38, v39 offset1:1
	v_add_u32_e32 v0, 0x18c8, v22
	ds_write2_b32 v0, v40, v41 offset1:1
	v_add_u32_e32 v0, 0x1ce0, v22
	s_waitcnt vmcnt(0)
	ds_write2_b32 v0, v42, v43 offset1:1
	v_add_u32_e32 v0, 0x1ce8, v22
	ds_write2_b32 v0, v44, v45 offset1:1
	s_waitcnt lgkmcnt(0)
	ds_read2_b32 v[12:13], v24 offset0:33 offset1:41
	ds_read2_b32 v[14:15], v24 offset1:8
	ds_read2_b32 v[16:17], v24 offset0:66 offset1:74
	ds_read2_b32 v[18:19], v24 offset0:99 offset1:107
	ds_read2_b32 v[26:27], v24 offset0:132 offset1:140
	ds_read2_b32 v[28:29], v24 offset0:165 offset1:173
	ds_read2_b32 v[30:31], v24 offset0:198 offset1:206
	ds_read2_b32 v[32:33], v24 offset0:231 offset1:239
	v_ashrrev_i32_e32 v35, 31, v34
	v_lshlrev_b64 v[36:37], 11, v[34:35]
	s_waitcnt lgkmcnt(6)
	v_cvt_pk_bf16_f32 v8, v14, v12
	s_waitcnt lgkmcnt(4)
	v_cvt_pk_bf16_f32 v9, v16, v18
	s_waitcnt lgkmcnt(2)
	v_cvt_pk_bf16_f32 v10, v26, v28
	s_waitcnt lgkmcnt(0)
	v_cvt_pk_bf16_f32 v11, v30, v32
	v_lshl_add_u64 v[36:37], v[6:7], 0, v[36:37]
	v_add_u32_e32 v12, 8, v34
	global_store_dwordx4 v[36:37], v[8:11], off sc1
	v_add_u32_e32 v36, 16, v34
	v_ashrrev_i32_e32 v37, 31, v36
	v_cvt_pk_bf16_f32 v8, v15, v13
	v_ashrrev_i32_e32 v13, 31, v12
	v_lshlrev_b64 v[12:13], 11, v[12:13]
	v_cvt_pk_bf16_f32 v9, v17, v19
	v_cvt_pk_bf16_f32 v10, v27, v29
	v_cvt_pk_bf16_f32 v11, v31, v33
	v_lshl_add_u64 v[12:13], v[6:7], 0, v[12:13]
	global_store_dwordx4 v[12:13], v[8:11], off sc1
	ds_read2_b32 v[12:13], v24 offset0:49 offset1:57
	ds_read2_b32 v[14:15], v24 offset0:16 offset1:24
	ds_read2_b32 v[16:17], v24 offset0:82 offset1:90
	ds_read2_b32 v[18:19], v24 offset0:115 offset1:123
	ds_read2_b32 v[26:27], v24 offset0:148 offset1:156
	ds_read2_b32 v[28:29], v24 offset0:181 offset1:189
	ds_read2_b32 v[30:31], v24 offset0:214 offset1:222
	ds_read2_b32 v[32:33], v24 offset0:247 offset1:255
	v_lshlrev_b64 v[36:37], 11, v[36:37]
	s_waitcnt lgkmcnt(6)
	v_cvt_pk_bf16_f32 v8, v14, v12
	s_waitcnt lgkmcnt(4)
	v_cvt_pk_bf16_f32 v9, v16, v18
	s_waitcnt lgkmcnt(2)
	v_cvt_pk_bf16_f32 v10, v26, v28
	s_waitcnt lgkmcnt(0)
	v_cvt_pk_bf16_f32 v11, v30, v32
	v_lshl_add_u64 v[36:37], v[6:7], 0, v[36:37]
	v_add_u32_e32 v12, 24, v34
	global_store_dwordx4 v[36:37], v[8:11], off sc1
	s_nop 1
	v_cvt_pk_bf16_f32 v8, v15, v13
	v_ashrrev_i32_e32 v13, 31, v12
	v_lshlrev_b64 v[12:13], 11, v[12:13]
	v_cvt_pk_bf16_f32 v9, v17, v19
	v_cvt_pk_bf16_f32 v10, v27, v29
	v_cvt_pk_bf16_f32 v11, v31, v33
	v_lshl_add_u64 v[6:7], v[6:7], 0, v[12:13]
	global_store_dwordx4 v[6:7], v[8:11], off sc1
	s_waitcnt lgkmcnt(0)
	s_cbranch_execnz .LBB0_1152
	s_branch .LBB0_1151
